# layer-0 norm phase: two hand-written 64-row norm units per workgroup
# speedup vs baseline: 1.0071x; 1.0029x over previous
; DI unsigned pk2(float lo, float hi) { unsigned r; asm volatile("v_cvt_pk_bf16_f32 %0, %1, %2" : "=v"(r) : "v"(lo), "v"(hi)); return r; }
; DI float shx(float v, int m, int lane) { return __int_as_float(__builtin_amdgcn_ds_bpermute((lane ^ m) << 2, __float_as_int(v))); }
; DI void norm_rows(const Params& p, int layer, int row0, int nrows, int wstart, int wstride, int tid) {
;     ...
;   for (int rowa = row0 + wstart + wid; rowa < row0 + nrows; rowa += 2 * wstride) {
;     const int rowb = (rowa + wstride < row0 + nrows) ? rowa + wstride : rowa;
;     float4 va[4], vb[4]; float sa = 0.f, sb = 0.f;
; #pragma unroll
;     for (int i = 0; i < 4; ++i) { va[i] = *(const float4*)(xin + (size_t)rowa * DM + i * 256 + lane * 4); vb[i] = *(const float4*)(xin + (size_t)rowb * DM + i * 256 + lane * 4); }
; #pragma unroll
;     for (int i = 0; i < 4; ++i) { sa += va[i].x * va[i].x + va[i].y * va[i].y + va[i].z * va[i].z + va[i].w * va[i].w; sb += vb[i].x * vb[i].x + vb[i].y * vb[i].y + vb[i].z * vb[i].z + vb[i].w * vb[i].w; }
; #pragma unroll
;     for (int o = 32; o >= 1; o >>= 1) { sa += shx(sa, o, lane); sb += shx(sb, o, lane); }
; #pragma unroll
;     for (int rr = 0; rr < 2; ++rr) {
;       const int row = rr ? rowb : rowa; const float rinv = rsqrtf((rr ? sb : sa) * (1.0f / 1024.0f) + EPS);
;       if (layer < NLAYER) {
;         const int b = row >> 13; const float* md = modb + (size_t)(layer * 4 + b) * 3072; const float* g = p.norm_g + layer * 1024;
; #pragma unroll
;         for (int i = 0; i < 4; ++i) {
;           const float4 x4 = rr ? vb[i] : va[i];
;           const int e = i * 256 + lane * 4;
;           const float4 g4 = *(const float4*)(g + e), sh = *(const float4*)(md + e), sc = *(const float4*)(md + 1024 + e);
;           uint2 w;
;           w.x = pk2(x4.x * rinv * g4.x * (1.f + sc.x) + sh.x, x4.y * rinv * g4.y * (1.f + sc.y) + sh.y);
;           w.y = pk2(x4.z * rinv * g4.z * (1.f + sc.z) + sh.z, x4.w * rinv * g4.w * (1.f + sc.w) + sh.w);
;           *(uint2*)(h + wimg_off(row, e, DM)) = w;
; DI void norm_phase(const Params& p, int layer, int tid) { norm_rows(p, layer, 0, ROWS, blockIdx.x * 8, gridDim.x * 8, tid); }
.LBB0_91:
	s_cmp_lg_u32 s2, 0
	s_mov_b64 s[0:1], s[36:37]
	s_cbranch_scc1 .LBB0_148
	v_readlane_b32 s0, v253, 47
	v_readlane_b32 s4, v252, 2
	v_readlane_b32 s5, v252, 3
	v_readlane_b32 s6, v252, 8
	v_readlane_b32 s7, v252, 9
	v_readlane_b32 s8, v252, 22
	v_readlane_b32 s9, v252, 23
	v_readlane_b32 s18, v252, 48
	v_readlane_b32 s19, v252, 49
	s_lshl_b32 s0, s0, 3
	s_lshl_b32 s1, s0, 12
	s_add_u32 s4, s4, s1
	s_addc_u32 s5, s5, 0
	s_add_u32 s6, s6, 0
	s_addc_u32 s7, s7, 0
	s_lshr_b32 s1, s0, 13
	s_mul_i32 s1, s1, 0x3000
	s_add_u32 s8, s8, s1
	s_addc_u32 s9, s9, 0
	s_add_u32 s10, s8, 0x1000
	s_addc_u32 s11, s9, 0
	s_lshr_b32 s1, s0, 7
	s_lshl_b32 s1, s1, 18
	s_bfe_u32 s12, s0, 0x10006
	s_lshl_b32 s12, s12, 12
	s_add_u32 s1, s1, s12
	s_add_u32 s18, s18, s1
	s_addc_u32 s19, s19, 0
	v_and_b32_e32 v245, 63, v163
	v_lshrrev_b32_e32 v246, 6, v163
	v_lshlrev_b32_e32 v247, 2, v245
	v_xor_b32_e32 v236, 0x80, v247
	v_xor_b32_e32 v237, 0x40, v247
	v_xor_b32_e32 v238, 0x20, v247
	v_xor_b32_e32 v239, 0x10, v247
	v_xor_b32_e32 v240, 0x8, v247
	v_xor_b32_e32 v241, 0x4, v247
	v_lshlrev_b32_e32 v245, 4, v245
	v_lshl_add_u32 v242, v246, 12, v245
	v_and_b32_e32 v248, 63, v163
	v_lshrrev_b32_e32 v249, 3, v248
	v_and_b32_e32 v248, 7, v248
	v_lshlrev_b32_e32 v248, 3, v248
	v_lshlrev_b32_e32 v249, 13, v249
	v_lshl_add_u32 v249, v246, 6, v249
	v_add_u32_e32 v243, v249, v248
	v_xor_b32_e32 v248, 32, v248
	v_add_u32_e32 v244, v249, v248
	v_add_u32_e32 v244, 0x200, v244
	global_load_dwordx4 v[128:131], v245, s[6:7] offset:0
	global_load_dwordx4 v[132:135], v245, s[6:7] offset:1024
	global_load_dwordx4 v[136:139], v245, s[6:7] offset:2048
	global_load_dwordx4 v[140:143], v245, s[6:7] offset:3072
	global_load_dwordx4 v[144:147], v245, s[8:9] offset:0
	global_load_dwordx4 v[148:151], v245, s[8:9] offset:1024
	global_load_dwordx4 v[152:155], v245, s[8:9] offset:2048
	global_load_dwordx4 v[156:159], v245, s[8:9] offset:3072
	global_load_dwordx4 v[204:207], v245, s[10:11] offset:0
	global_load_dwordx4 v[208:211], v245, s[10:11] offset:1024
	global_load_dwordx4 v[212:215], v245, s[10:11] offset:2048
	global_load_dwordx4 v[216:219], v245, s[10:11] offset:3072
	global_load_dwordx4 v[0:3], v242, s[4:5] offset:0
	global_load_dwordx4 v[4:7], v242, s[4:5] offset:1024
	global_load_dwordx4 v[8:11], v242, s[4:5] offset:2048
	global_load_dwordx4 v[12:15], v242, s[4:5] offset:3072
	s_add_u32 s4, s4, 0x8000
	s_addc_u32 s5, s5, 0
	global_load_dwordx4 v[16:19], v242, s[4:5] offset:0
	global_load_dwordx4 v[20:23], v242, s[4:5] offset:1024
	global_load_dwordx4 v[24:27], v242, s[4:5] offset:2048
	global_load_dwordx4 v[28:31], v242, s[4:5] offset:3072
	s_add_u32 s4, s4, 0x8000
	s_addc_u32 s5, s5, 0
	global_load_dwordx4 v[32:35], v242, s[4:5] offset:0
	global_load_dwordx4 v[36:39], v242, s[4:5] offset:1024
	global_load_dwordx4 v[40:43], v242, s[4:5] offset:2048
	global_load_dwordx4 v[44:47], v242, s[4:5] offset:3072
	s_add_u32 s4, s4, 0x8000
	s_addc_u32 s5, s5, 0
	global_load_dwordx4 v[48:51], v242, s[4:5] offset:0
	global_load_dwordx4 v[52:55], v242, s[4:5] offset:1024
	global_load_dwordx4 v[56:59], v242, s[4:5] offset:2048
	global_load_dwordx4 v[60:63], v242, s[4:5] offset:3072
	s_add_u32 s4, s4, 0x8000
	s_addc_u32 s5, s5, 0
	global_load_dwordx4 v[64:67], v242, s[4:5] offset:0
	global_load_dwordx4 v[68:71], v242, s[4:5] offset:1024
	global_load_dwordx4 v[72:75], v242, s[4:5] offset:2048
	global_load_dwordx4 v[76:79], v242, s[4:5] offset:3072
	s_add_u32 s4, s4, 0x8000
	s_addc_u32 s5, s5, 0
	global_load_dwordx4 v[80:83], v242, s[4:5] offset:0
	global_load_dwordx4 v[84:87], v242, s[4:5] offset:1024
	global_load_dwordx4 v[88:91], v242, s[4:5] offset:2048
	global_load_dwordx4 v[92:95], v242, s[4:5] offset:3072
	s_add_u32 s4, s4, 0x8000
	s_addc_u32 s5, s5, 0
	global_load_dwordx4 v[96:99], v242, s[4:5] offset:0
	global_load_dwordx4 v[100:103], v242, s[4:5] offset:1024
	global_load_dwordx4 v[104:107], v242, s[4:5] offset:2048
	global_load_dwordx4 v[108:111], v242, s[4:5] offset:3072
	s_add_u32 s4, s4, 0x8000
	s_addc_u32 s5, s5, 0
	global_load_dwordx4 v[112:115], v242, s[4:5] offset:0
	global_load_dwordx4 v[116:119], v242, s[4:5] offset:1024
	global_load_dwordx4 v[120:123], v242, s[4:5] offset:2048
	global_load_dwordx4 v[124:127], v242, s[4:5] offset:3072
	s_add_u32 s20, s18, 0x10000
	s_addc_u32 s21, s19, 0
	s_add_u32 s22, s18, 0x20000
	s_addc_u32 s23, s19, 0
	s_add_u32 s24, s18, 0x30000
	s_addc_u32 s25, s19, 0
	s_mov_b32 s26, 0x3a800000
	s_waitcnt vmcnt(24)
	v_add_f32_e32 v204, 1.0, v204
	v_add_f32_e32 v205, 1.0, v205
	v_add_f32_e32 v206, 1.0, v206
	v_add_f32_e32 v207, 1.0, v207
	v_add_f32_e32 v208, 1.0, v208
	v_add_f32_e32 v209, 1.0, v209
	v_add_f32_e32 v210, 1.0, v210
	v_add_f32_e32 v211, 1.0, v211
	v_add_f32_e32 v212, 1.0, v212
	v_add_f32_e32 v213, 1.0, v213
	v_add_f32_e32 v214, 1.0, v214
	v_add_f32_e32 v215, 1.0, v215
	v_add_f32_e32 v216, 1.0, v216
	v_add_f32_e32 v217, 1.0, v217
	v_add_f32_e32 v218, 1.0, v218
	v_add_f32_e32 v219, 1.0, v219
	v_mul_f32_e32 v220, v1, v1
	v_mul_f32_e32 v224, v17, v17
	v_fmac_f32_e32 v220, v0, v0
	v_fmac_f32_e32 v224, v16, v16
	v_fmac_f32_e32 v220, v2, v2
	v_fmac_f32_e32 v224, v18, v18
	v_fmac_f32_e32 v220, v3, v3
	v_fmac_f32_e32 v224, v19, v19
	v_mul_f32_e32 v221, v5, v5
	v_mul_f32_e32 v225, v21, v21
	v_fmac_f32_e32 v221, v4, v4
	v_fmac_f32_e32 v225, v20, v20
	v_fmac_f32_e32 v221, v6, v6
	v_fmac_f32_e32 v225, v22, v22
	v_fmac_f32_e32 v221, v7, v7
	v_fmac_f32_e32 v225, v23, v23
	v_mul_f32_e32 v222, v9, v9
	v_mul_f32_e32 v226, v25, v25
	v_fmac_f32_e32 v222, v8, v8
	v_fmac_f32_e32 v226, v24, v24
	v_fmac_f32_e32 v222, v10, v10
	v_fmac_f32_e32 v226, v26, v26
	v_fmac_f32_e32 v222, v11, v11
	v_fmac_f32_e32 v226, v27, v27
	v_mul_f32_e32 v223, v13, v13
	v_mul_f32_e32 v227, v29, v29
	v_fmac_f32_e32 v223, v12, v12
	v_fmac_f32_e32 v227, v28, v28
	v_fmac_f32_e32 v223, v14, v14
	v_fmac_f32_e32 v227, v30, v30
	v_fmac_f32_e32 v223, v15, v15
	v_fmac_f32_e32 v227, v31, v31
	v_add_f32_e32 v228, v220, v221
	v_add_f32_e32 v229, v224, v225
	v_add_f32_e32 v228, v228, v222
	v_add_f32_e32 v229, v229, v226
	v_add_f32_e32 v228, v228, v223
	v_add_f32_e32 v229, v229, v227
	ds_bpermute_b32 v230, v236, v228
	ds_bpermute_b32 v231, v236, v229
	s_waitcnt lgkmcnt(0)
; DI unsigned pk2(float lo, float hi) { unsigned r; asm volatile("v_cvt_pk_bf16_f32 %0, %1, %2" : "=v"(r) : "v"(lo), "v"(hi)); return r; }
; DI float shx(float v, int m, int lane) { return __int_as_float(__builtin_amdgcn_ds_bpermute((lane ^ m) << 2, __float_as_int(v))); }
; DI void norm_rows(const Params& p, int layer, int row0, int nrows, int wstart, int wstride, int tid) {
;     ...
;     for (int i = 0; i < 4; ++i) { va[i] = *(const float4*)(xin + (size_t)rowa * DM + i * 256 + lane * 4); vb[i] = *(const float4*)(xin + (size_t)rowb * DM + i * 256 + lane * 4); }
; #pragma unroll
;     for (int i = 0; i < 4; ++i) { sa += va[i].x * va[i].x + va[i].y * va[i].y + va[i].z * va[i].z + va[i].w * va[i].w; sb += vb[i].x * vb[i].x + vb[i].y * vb[i].y + vb[i].z * vb[i].z + vb[i].w * vb[i].w; }
; #pragma unroll
;     for (int o = 32; o >= 1; o >>= 1) { sa += shx(sa, o, lane); sb += shx(sb, o, lane); }
; #pragma unroll
;     for (int rr = 0; rr < 2; ++rr) {
;       const int row = rr ? rowb : rowa; const float rinv = rsqrtf((rr ? sb : sa) * (1.0f / 1024.0f) + EPS);
;       if (layer < NLAYER) {
;         const int b = row >> 13; const float* md = modb + (size_t)(layer * 4 + b) * 3072; const float* g = p.norm_g + layer * 1024;
; #pragma unroll
;         for (int i = 0; i < 4; ++i) {
;           const float4 x4 = rr ? vb[i] : va[i];
;           const int e = i * 256 + lane * 4;
;           const float4 g4 = *(const float4*)(g + e), sh = *(const float4*)(md + e), sc = *(const float4*)(md + 1024 + e);
;           uint2 w;
;           w.x = pk2(x4.x * rinv * g4.x * (1.f + sc.x) + sh.x, x4.y * rinv * g4.y * (1.f + sc.y) + sh.y);
;           w.y = pk2(x4.z * rinv * g4.z * (1.f + sc.z) + sh.z, x4.w * rinv * g4.w * (1.f + sc.w) + sh.w);
;           *(uint2*)(h + wimg_off(row, e, DM)) = w;
	v_add_f32_e32 v228, v228, v230
	v_add_f32_e32 v229, v229, v231
	ds_bpermute_b32 v230, v237, v228
	ds_bpermute_b32 v231, v237, v229
	s_waitcnt lgkmcnt(0)
	v_add_f32_e32 v228, v228, v230
	v_add_f32_e32 v229, v229, v231
	ds_bpermute_b32 v230, v238, v228
	ds_bpermute_b32 v231, v238, v229
	s_waitcnt lgkmcnt(0)
	v_add_f32_e32 v228, v228, v230
	v_add_f32_e32 v229, v229, v231
	ds_bpermute_b32 v230, v239, v228
	ds_bpermute_b32 v231, v239, v229
	s_waitcnt lgkmcnt(0)
	v_add_f32_e32 v228, v228, v230
	v_add_f32_e32 v229, v229, v231
	ds_bpermute_b32 v230, v240, v228
	ds_bpermute_b32 v231, v240, v229
	s_waitcnt lgkmcnt(0)
	v_add_f32_e32 v228, v228, v230
	v_add_f32_e32 v229, v229, v231
	ds_bpermute_b32 v230, v241, v228
	ds_bpermute_b32 v231, v241, v229
	s_waitcnt lgkmcnt(0)
	v_add_f32_e32 v228, v228, v230
	v_add_f32_e32 v229, v229, v231
	v_fma_f32 v228, v228, s26, v162
	v_fma_f32 v229, v229, s26, v162
	v_rsq_f32_e32 v232, v228
	v_rsq_f32_e32 v233, v229
	s_nop 0
	v_mul_f32_e32 v0, v0, v232
	v_mul_f32_e32 v1, v1, v232
	v_mul_f32_e32 v2, v2, v232
	v_mul_f32_e32 v3, v3, v232
	v_mul_f32_e32 v0, v128, v0
	v_mul_f32_e32 v1, v129, v1
	v_mul_f32_e32 v2, v130, v2
	v_mul_f32_e32 v3, v131, v3
	v_fma_f32 v0, v0, v204, v144
	v_fma_f32 v1, v1, v205, v145
	v_fma_f32 v2, v2, v206, v146
	v_fma_f32 v3, v3, v207, v147
	v_cvt_pk_bf16_f32 v234, v0, v1
	v_cvt_pk_bf16_f32 v235, v2, v3
	s_nop 0
	global_store_dwordx2 v243, v[234:235], s[18:19] offset:0
	v_mul_f32_e32 v4, v4, v232
	v_mul_f32_e32 v5, v5, v232
	v_mul_f32_e32 v6, v6, v232
	v_mul_f32_e32 v7, v7, v232
	v_mul_f32_e32 v4, v132, v4
	v_mul_f32_e32 v5, v133, v5
	v_mul_f32_e32 v6, v134, v6
	v_mul_f32_e32 v7, v135, v7
	v_fma_f32 v4, v4, v208, v148
	v_fma_f32 v5, v5, v209, v149
	v_fma_f32 v6, v6, v210, v150
	v_fma_f32 v7, v7, v211, v151
	v_cvt_pk_bf16_f32 v234, v4, v5
	v_cvt_pk_bf16_f32 v235, v6, v7
	s_nop 0
	global_store_dwordx2 v243, v[234:235], s[20:21] offset:0
	v_mul_f32_e32 v8, v8, v232
	v_mul_f32_e32 v9, v9, v232
	v_mul_f32_e32 v10, v10, v232
	v_mul_f32_e32 v11, v11, v232
	v_mul_f32_e32 v8, v136, v8
	v_mul_f32_e32 v9, v137, v9
	v_mul_f32_e32 v10, v138, v10
	v_mul_f32_e32 v11, v139, v11
	v_fma_f32 v8, v8, v212, v152
	v_fma_f32 v9, v9, v213, v153
	v_fma_f32 v10, v10, v214, v154
	v_fma_f32 v11, v11, v215, v155
	v_cvt_pk_bf16_f32 v234, v8, v9
	v_cvt_pk_bf16_f32 v235, v10, v11
	s_nop 0
	global_store_dwordx2 v243, v[234:235], s[22:23] offset:0
	v_mul_f32_e32 v12, v12, v232
	v_mul_f32_e32 v13, v13, v232
	v_mul_f32_e32 v14, v14, v232
	v_mul_f32_e32 v15, v15, v232
	v_mul_f32_e32 v12, v140, v12
	v_mul_f32_e32 v13, v141, v13
	v_mul_f32_e32 v14, v142, v14
	v_mul_f32_e32 v15, v143, v15
	v_fma_f32 v12, v12, v216, v156
	v_fma_f32 v13, v13, v217, v157
	v_fma_f32 v14, v14, v218, v158
	v_fma_f32 v15, v15, v219, v159
	v_cvt_pk_bf16_f32 v234, v12, v13
	v_cvt_pk_bf16_f32 v235, v14, v15
	s_nop 0
	global_store_dwordx2 v243, v[234:235], s[24:25] offset:0
	v_mul_f32_e32 v16, v16, v233
	v_mul_f32_e32 v17, v17, v233
	v_mul_f32_e32 v18, v18, v233
	v_mul_f32_e32 v19, v19, v233
	v_mul_f32_e32 v16, v128, v16
	v_mul_f32_e32 v17, v129, v17
	v_mul_f32_e32 v18, v130, v18
	v_mul_f32_e32 v19, v131, v19
	v_fma_f32 v16, v16, v204, v144
	v_fma_f32 v17, v17, v205, v145
	v_fma_f32 v18, v18, v206, v146
	v_fma_f32 v19, v19, v207, v147
	v_cvt_pk_bf16_f32 v234, v16, v17
	v_cvt_pk_bf16_f32 v235, v18, v19
	s_nop 0
	global_store_dwordx2 v244, v[234:235], s[18:19] offset:0
	v_mul_f32_e32 v20, v20, v233
	v_mul_f32_e32 v21, v21, v233
	v_mul_f32_e32 v22, v22, v233
	v_mul_f32_e32 v23, v23, v233
	v_mul_f32_e32 v20, v132, v20
	v_mul_f32_e32 v21, v133, v21
	v_mul_f32_e32 v22, v134, v22
	v_mul_f32_e32 v23, v135, v23
	v_fma_f32 v20, v20, v208, v148
	v_fma_f32 v21, v21, v209, v149
	v_fma_f32 v22, v22, v210, v150
	v_fma_f32 v23, v23, v211, v151
	v_cvt_pk_bf16_f32 v234, v20, v21
	v_cvt_pk_bf16_f32 v235, v22, v23
	s_nop 0
	global_store_dwordx2 v244, v[234:235], s[20:21] offset:0
	v_mul_f32_e32 v24, v24, v233
	v_mul_f32_e32 v25, v25, v233
	v_mul_f32_e32 v26, v26, v233
	v_mul_f32_e32 v27, v27, v233
	v_mul_f32_e32 v24, v136, v24
	v_mul_f32_e32 v25, v137, v25
	v_mul_f32_e32 v26, v138, v26
	v_mul_f32_e32 v27, v139, v27
	v_fma_f32 v24, v24, v212, v152
	v_fma_f32 v25, v25, v213, v153
	v_fma_f32 v26, v26, v214, v154
	v_fma_f32 v27, v27, v215, v155
	v_cvt_pk_bf16_f32 v234, v24, v25
	v_cvt_pk_bf16_f32 v235, v26, v27
	s_nop 0
	global_store_dwordx2 v244, v[234:235], s[22:23] offset:0
	v_mul_f32_e32 v28, v28, v233
	v_mul_f32_e32 v29, v29, v233
	v_mul_f32_e32 v30, v30, v233
	v_mul_f32_e32 v31, v31, v233
	v_mul_f32_e32 v28, v140, v28
	v_mul_f32_e32 v29, v141, v29
	v_mul_f32_e32 v30, v142, v30
	v_mul_f32_e32 v31, v143, v31
	v_fma_f32 v28, v28, v216, v156
	v_fma_f32 v29, v29, v217, v157
	v_fma_f32 v30, v30, v218, v158
	v_fma_f32 v31, v31, v219, v159
	v_cvt_pk_bf16_f32 v234, v28, v29
	v_cvt_pk_bf16_f32 v235, v30, v31
	s_nop 0
	global_store_dwordx2 v244, v[234:235], s[24:25] offset:0
	s_waitcnt vmcnt(24)
	v_mul_f32_e32 v220, v33, v33
	v_mul_f32_e32 v224, v49, v49
	v_fmac_f32_e32 v220, v32, v32
	v_fmac_f32_e32 v224, v48, v48
	v_fmac_f32_e32 v220, v34, v34
	v_fmac_f32_e32 v224, v50, v50
	v_fmac_f32_e32 v220, v35, v35
	v_fmac_f32_e32 v224, v51, v51
	v_mul_f32_e32 v221, v37, v37
	v_mul_f32_e32 v225, v53, v53
	v_fmac_f32_e32 v221, v36, v36
	v_fmac_f32_e32 v225, v52, v52
	v_fmac_f32_e32 v221, v38, v38
	v_fmac_f32_e32 v225, v54, v54
	v_fmac_f32_e32 v221, v39, v39
	v_fmac_f32_e32 v225, v55, v55
	v_mul_f32_e32 v222, v41, v41
	v_mul_f32_e32 v226, v57, v57
	v_fmac_f32_e32 v222, v40, v40
	v_fmac_f32_e32 v226, v56, v56
	v_fmac_f32_e32 v222, v42, v42
	v_fmac_f32_e32 v226, v58, v58
	v_fmac_f32_e32 v222, v43, v43
	v_fmac_f32_e32 v226, v59, v59
	v_mul_f32_e32 v223, v45, v45
	v_mul_f32_e32 v227, v61, v61
	v_fmac_f32_e32 v223, v44, v44
	v_fmac_f32_e32 v227, v60, v60
	v_fmac_f32_e32 v223, v46, v46
	v_fmac_f32_e32 v227, v62, v62
	v_fmac_f32_e32 v223, v47, v47
	v_fmac_f32_e32 v227, v63, v63
	v_add_f32_e32 v228, v220, v221
	v_add_f32_e32 v229, v224, v225
	v_add_f32_e32 v228, v228, v222
	v_add_f32_e32 v229, v229, v226
	v_add_f32_e32 v228, v228, v223
	v_add_f32_e32 v229, v229, v227
	ds_bpermute_b32 v230, v236, v228
	ds_bpermute_b32 v231, v236, v229
	s_waitcnt lgkmcnt(0)
; DI unsigned pk2(float lo, float hi) { unsigned r; asm volatile("v_cvt_pk_bf16_f32 %0, %1, %2" : "=v"(r) : "v"(lo), "v"(hi)); return r; }
; DI float shx(float v, int m, int lane) { return __int_as_float(__builtin_amdgcn_ds_bpermute((lane ^ m) << 2, __float_as_int(v))); }
; DI void norm_rows(const Params& p, int layer, int row0, int nrows, int wstart, int wstride, int tid) {
;     ...
;     for (int i = 0; i < 4; ++i) { sa += va[i].x * va[i].x + va[i].y * va[i].y + va[i].z * va[i].z + va[i].w * va[i].w; sb += vb[i].x * vb[i].x + vb[i].y * vb[i].y + vb[i].z * vb[i].z + vb[i].w * vb[i].w; }
; #pragma unroll
;     for (int o = 32; o >= 1; o >>= 1) { sa += shx(sa, o, lane); sb += shx(sb, o, lane); }
; #pragma unroll
;     for (int rr = 0; rr < 2; ++rr) {
;       const int row = rr ? rowb : rowa; const float rinv = rsqrtf((rr ? sb : sa) * (1.0f / 1024.0f) + EPS);
;       if (layer < NLAYER) {
;         const int b = row >> 13; const float* md = modb + (size_t)(layer * 4 + b) * 3072; const float* g = p.norm_g + layer * 1024;
; #pragma unroll
;         for (int i = 0; i < 4; ++i) {
;           const float4 x4 = rr ? vb[i] : va[i];
;           const int e = i * 256 + lane * 4;
;           const float4 g4 = *(const float4*)(g + e), sh = *(const float4*)(md + e), sc = *(const float4*)(md + 1024 + e);
;           uint2 w;
;           w.x = pk2(x4.x * rinv * g4.x * (1.f + sc.x) + sh.x, x4.y * rinv * g4.y * (1.f + sc.y) + sh.y);
;           w.y = pk2(x4.z * rinv * g4.z * (1.f + sc.z) + sh.z, x4.w * rinv * g4.w * (1.f + sc.w) + sh.w);
;           *(uint2*)(h + wimg_off(row, e, DM)) = w;
	v_add_f32_e32 v228, v228, v230
	v_add_f32_e32 v229, v229, v231
	ds_bpermute_b32 v230, v237, v228
	ds_bpermute_b32 v231, v237, v229
	s_waitcnt lgkmcnt(0)
	v_add_f32_e32 v228, v228, v230
	v_add_f32_e32 v229, v229, v231
	ds_bpermute_b32 v230, v238, v228
	ds_bpermute_b32 v231, v238, v229
	s_waitcnt lgkmcnt(0)
	v_add_f32_e32 v228, v228, v230
	v_add_f32_e32 v229, v229, v231
	ds_bpermute_b32 v230, v239, v228
	ds_bpermute_b32 v231, v239, v229
	s_waitcnt lgkmcnt(0)
	v_add_f32_e32 v228, v228, v230
	v_add_f32_e32 v229, v229, v231
	ds_bpermute_b32 v230, v240, v228
	ds_bpermute_b32 v231, v240, v229
	s_waitcnt lgkmcnt(0)
	v_add_f32_e32 v228, v228, v230
	v_add_f32_e32 v229, v229, v231
	ds_bpermute_b32 v230, v241, v228
	ds_bpermute_b32 v231, v241, v229
	s_waitcnt lgkmcnt(0)
	v_add_f32_e32 v228, v228, v230
	v_add_f32_e32 v229, v229, v231
	v_fma_f32 v228, v228, s26, v162
	v_fma_f32 v229, v229, s26, v162
	v_rsq_f32_e32 v232, v228
	v_rsq_f32_e32 v233, v229
	s_nop 0
	v_mul_f32_e32 v32, v32, v232
	v_mul_f32_e32 v33, v33, v232
	v_mul_f32_e32 v34, v34, v232
	v_mul_f32_e32 v35, v35, v232
	v_mul_f32_e32 v32, v128, v32
	v_mul_f32_e32 v33, v129, v33
	v_mul_f32_e32 v34, v130, v34
	v_mul_f32_e32 v35, v131, v35
	v_fma_f32 v32, v32, v204, v144
	v_fma_f32 v33, v33, v205, v145
	v_fma_f32 v34, v34, v206, v146
	v_fma_f32 v35, v35, v207, v147
	v_cvt_pk_bf16_f32 v234, v32, v33
	v_cvt_pk_bf16_f32 v235, v34, v35
	s_nop 0
	global_store_dwordx2 v243, v[234:235], s[18:19] offset:1024
	v_mul_f32_e32 v36, v36, v232
	v_mul_f32_e32 v37, v37, v232
	v_mul_f32_e32 v38, v38, v232
	v_mul_f32_e32 v39, v39, v232
	v_mul_f32_e32 v36, v132, v36
	v_mul_f32_e32 v37, v133, v37
	v_mul_f32_e32 v38, v134, v38
	v_mul_f32_e32 v39, v135, v39
	v_fma_f32 v36, v36, v208, v148
	v_fma_f32 v37, v37, v209, v149
	v_fma_f32 v38, v38, v210, v150
	v_fma_f32 v39, v39, v211, v151
	v_cvt_pk_bf16_f32 v234, v36, v37
	v_cvt_pk_bf16_f32 v235, v38, v39
	s_nop 0
	global_store_dwordx2 v243, v[234:235], s[20:21] offset:1024
	v_mul_f32_e32 v40, v40, v232
	v_mul_f32_e32 v41, v41, v232
	v_mul_f32_e32 v42, v42, v232
	v_mul_f32_e32 v43, v43, v232
	v_mul_f32_e32 v40, v136, v40
	v_mul_f32_e32 v41, v137, v41
	v_mul_f32_e32 v42, v138, v42
	v_mul_f32_e32 v43, v139, v43
	v_fma_f32 v40, v40, v212, v152
	v_fma_f32 v41, v41, v213, v153
	v_fma_f32 v42, v42, v214, v154
	v_fma_f32 v43, v43, v215, v155
	v_cvt_pk_bf16_f32 v234, v40, v41
	v_cvt_pk_bf16_f32 v235, v42, v43
	s_nop 0
	global_store_dwordx2 v243, v[234:235], s[22:23] offset:1024
	v_mul_f32_e32 v44, v44, v232
	v_mul_f32_e32 v45, v45, v232
	v_mul_f32_e32 v46, v46, v232
	v_mul_f32_e32 v47, v47, v232
	v_mul_f32_e32 v44, v140, v44
	v_mul_f32_e32 v45, v141, v45
	v_mul_f32_e32 v46, v142, v46
	v_mul_f32_e32 v47, v143, v47
	v_fma_f32 v44, v44, v216, v156
	v_fma_f32 v45, v45, v217, v157
	v_fma_f32 v46, v46, v218, v158
	v_fma_f32 v47, v47, v219, v159
	v_cvt_pk_bf16_f32 v234, v44, v45
	v_cvt_pk_bf16_f32 v235, v46, v47
	s_nop 0
	global_store_dwordx2 v243, v[234:235], s[24:25] offset:1024
	v_mul_f32_e32 v48, v48, v233
	v_mul_f32_e32 v49, v49, v233
	v_mul_f32_e32 v50, v50, v233
	v_mul_f32_e32 v51, v51, v233
	v_mul_f32_e32 v48, v128, v48
	v_mul_f32_e32 v49, v129, v49
	v_mul_f32_e32 v50, v130, v50
	v_mul_f32_e32 v51, v131, v51
	v_fma_f32 v48, v48, v204, v144
	v_fma_f32 v49, v49, v205, v145
	v_fma_f32 v50, v50, v206, v146
	v_fma_f32 v51, v51, v207, v147
	v_cvt_pk_bf16_f32 v234, v48, v49
	v_cvt_pk_bf16_f32 v235, v50, v51
	s_nop 0
	global_store_dwordx2 v244, v[234:235], s[18:19] offset:1024
	v_mul_f32_e32 v52, v52, v233
	v_mul_f32_e32 v53, v53, v233
	v_mul_f32_e32 v54, v54, v233
	v_mul_f32_e32 v55, v55, v233
	v_mul_f32_e32 v52, v132, v52
	v_mul_f32_e32 v53, v133, v53
	v_mul_f32_e32 v54, v134, v54
	v_mul_f32_e32 v55, v135, v55
	v_fma_f32 v52, v52, v208, v148
	v_fma_f32 v53, v53, v209, v149
	v_fma_f32 v54, v54, v210, v150
	v_fma_f32 v55, v55, v211, v151
	v_cvt_pk_bf16_f32 v234, v52, v53
	v_cvt_pk_bf16_f32 v235, v54, v55
	s_nop 0
	global_store_dwordx2 v244, v[234:235], s[20:21] offset:1024
	v_mul_f32_e32 v56, v56, v233
	v_mul_f32_e32 v57, v57, v233
	v_mul_f32_e32 v58, v58, v233
	v_mul_f32_e32 v59, v59, v233
	v_mul_f32_e32 v56, v136, v56
	v_mul_f32_e32 v57, v137, v57
	v_mul_f32_e32 v58, v138, v58
	v_mul_f32_e32 v59, v139, v59
	v_fma_f32 v56, v56, v212, v152
	v_fma_f32 v57, v57, v213, v153
	v_fma_f32 v58, v58, v214, v154
	v_fma_f32 v59, v59, v215, v155
	v_cvt_pk_bf16_f32 v234, v56, v57
	v_cvt_pk_bf16_f32 v235, v58, v59
	s_nop 0
	global_store_dwordx2 v244, v[234:235], s[22:23] offset:1024
	v_mul_f32_e32 v60, v60, v233
	v_mul_f32_e32 v61, v61, v233
	v_mul_f32_e32 v62, v62, v233
	v_mul_f32_e32 v63, v63, v233
	v_mul_f32_e32 v60, v140, v60
	v_mul_f32_e32 v61, v141, v61
	v_mul_f32_e32 v62, v142, v62
	v_mul_f32_e32 v63, v143, v63
	v_fma_f32 v60, v60, v216, v156
	v_fma_f32 v61, v61, v217, v157
	v_fma_f32 v62, v62, v218, v158
	v_fma_f32 v63, v63, v219, v159
	v_cvt_pk_bf16_f32 v234, v60, v61
	v_cvt_pk_bf16_f32 v235, v62, v63
	s_nop 0
	global_store_dwordx2 v244, v[234:235], s[24:25] offset:1024
	s_waitcnt vmcnt(24)
; DI unsigned pk2(float lo, float hi) { unsigned r; asm volatile("v_cvt_pk_bf16_f32 %0, %1, %2" : "=v"(r) : "v"(lo), "v"(hi)); return r; }
; DI float shx(float v, int m, int lane) { return __int_as_float(__builtin_amdgcn_ds_bpermute((lane ^ m) << 2, __float_as_int(v))); }
; DI void norm_rows(const Params& p, int layer, int row0, int nrows, int wstart, int wstride, int tid) {
;     ...
;     for (int i = 0; i < 4; ++i) { sa += va[i].x * va[i].x + va[i].y * va[i].y + va[i].z * va[i].z + va[i].w * va[i].w; sb += vb[i].x * vb[i].x + vb[i].y * vb[i].y + vb[i].z * vb[i].z + vb[i].w * vb[i].w; }
; #pragma unroll
;     for (int o = 32; o >= 1; o >>= 1) { sa += shx(sa, o, lane); sb += shx(sb, o, lane); }
; #pragma unroll
;     for (int rr = 0; rr < 2; ++rr) {
;       const int row = rr ? rowb : rowa; const float rinv = rsqrtf((rr ? sb : sa) * (1.0f / 1024.0f) + EPS);
;       if (layer < NLAYER) {
;         const int b = row >> 13; const float* md = modb + (size_t)(layer * 4 + b) * 3072; const float* g = p.norm_g + layer * 1024;
; #pragma unroll
;         for (int i = 0; i < 4; ++i) {
;           const float4 x4 = rr ? vb[i] : va[i];
;           const int e = i * 256 + lane * 4;
;           const float4 g4 = *(const float4*)(g + e), sh = *(const float4*)(md + e), sc = *(const float4*)(md + 1024 + e);
;           uint2 w;
;           w.x = pk2(x4.x * rinv * g4.x * (1.f + sc.x) + sh.x, x4.y * rinv * g4.y * (1.f + sc.y) + sh.y);
;           w.y = pk2(x4.z * rinv * g4.z * (1.f + sc.z) + sh.z, x4.w * rinv * g4.w * (1.f + sc.w) + sh.w);
;           *(uint2*)(h + wimg_off(row, e, DM)) = w;
	v_mul_f32_e32 v220, v65, v65
	v_mul_f32_e32 v224, v81, v81
	v_fmac_f32_e32 v220, v64, v64
	v_fmac_f32_e32 v224, v80, v80
	v_fmac_f32_e32 v220, v66, v66
	v_fmac_f32_e32 v224, v82, v82
	v_fmac_f32_e32 v220, v67, v67
	v_fmac_f32_e32 v224, v83, v83
	v_mul_f32_e32 v221, v69, v69
	v_mul_f32_e32 v225, v85, v85
	v_fmac_f32_e32 v221, v68, v68
	v_fmac_f32_e32 v225, v84, v84
	v_fmac_f32_e32 v221, v70, v70
	v_fmac_f32_e32 v225, v86, v86
	v_fmac_f32_e32 v221, v71, v71
	v_fmac_f32_e32 v225, v87, v87
	v_mul_f32_e32 v222, v73, v73
	v_mul_f32_e32 v226, v89, v89
	v_fmac_f32_e32 v222, v72, v72
	v_fmac_f32_e32 v226, v88, v88
	v_fmac_f32_e32 v222, v74, v74
	v_fmac_f32_e32 v226, v90, v90
	v_fmac_f32_e32 v222, v75, v75
	v_fmac_f32_e32 v226, v91, v91
	v_mul_f32_e32 v223, v77, v77
	v_mul_f32_e32 v227, v93, v93
	v_fmac_f32_e32 v223, v76, v76
	v_fmac_f32_e32 v227, v92, v92
	v_fmac_f32_e32 v223, v78, v78
	v_fmac_f32_e32 v227, v94, v94
	v_fmac_f32_e32 v223, v79, v79
	v_fmac_f32_e32 v227, v95, v95
	v_add_f32_e32 v228, v220, v221
	v_add_f32_e32 v229, v224, v225
	v_add_f32_e32 v228, v228, v222
	v_add_f32_e32 v229, v229, v226
	v_add_f32_e32 v228, v228, v223
	v_add_f32_e32 v229, v229, v227
	ds_bpermute_b32 v230, v236, v228
	ds_bpermute_b32 v231, v236, v229
	s_waitcnt lgkmcnt(0)
	v_add_f32_e32 v228, v228, v230
	v_add_f32_e32 v229, v229, v231
	ds_bpermute_b32 v230, v237, v228
	ds_bpermute_b32 v231, v237, v229
	s_waitcnt lgkmcnt(0)
	v_add_f32_e32 v228, v228, v230
	v_add_f32_e32 v229, v229, v231
	ds_bpermute_b32 v230, v238, v228
	ds_bpermute_b32 v231, v238, v229
	s_waitcnt lgkmcnt(0)
	v_add_f32_e32 v228, v228, v230
	v_add_f32_e32 v229, v229, v231
	ds_bpermute_b32 v230, v239, v228
	ds_bpermute_b32 v231, v239, v229
	s_waitcnt lgkmcnt(0)
	v_add_f32_e32 v228, v228, v230
	v_add_f32_e32 v229, v229, v231
	ds_bpermute_b32 v230, v240, v228
	ds_bpermute_b32 v231, v240, v229
	s_waitcnt lgkmcnt(0)
	v_add_f32_e32 v228, v228, v230
	v_add_f32_e32 v229, v229, v231
	ds_bpermute_b32 v230, v241, v228
	ds_bpermute_b32 v231, v241, v229
	s_waitcnt lgkmcnt(0)
	v_add_f32_e32 v228, v228, v230
	v_add_f32_e32 v229, v229, v231
	v_fma_f32 v228, v228, s26, v162
	v_fma_f32 v229, v229, s26, v162
	v_rsq_f32_e32 v232, v228
	v_rsq_f32_e32 v233, v229
	s_nop 0
	v_mul_f32_e32 v64, v64, v232
	v_mul_f32_e32 v65, v65, v232
	v_mul_f32_e32 v66, v66, v232
	v_mul_f32_e32 v67, v67, v232
	v_mul_f32_e32 v64, v128, v64
	v_mul_f32_e32 v65, v129, v65
	v_mul_f32_e32 v66, v130, v66
	v_mul_f32_e32 v67, v131, v67
	v_fma_f32 v64, v64, v204, v144
	v_fma_f32 v65, v65, v205, v145
	v_fma_f32 v66, v66, v206, v146
	v_fma_f32 v67, v67, v207, v147
	v_cvt_pk_bf16_f32 v234, v64, v65
	v_cvt_pk_bf16_f32 v235, v66, v67
	s_nop 0
	global_store_dwordx2 v243, v[234:235], s[18:19] offset:2048
	v_mul_f32_e32 v68, v68, v232
	v_mul_f32_e32 v69, v69, v232
	v_mul_f32_e32 v70, v70, v232
	v_mul_f32_e32 v71, v71, v232
	v_mul_f32_e32 v68, v132, v68
	v_mul_f32_e32 v69, v133, v69
	v_mul_f32_e32 v70, v134, v70
	v_mul_f32_e32 v71, v135, v71
	v_fma_f32 v68, v68, v208, v148
	v_fma_f32 v69, v69, v209, v149
	v_fma_f32 v70, v70, v210, v150
	v_fma_f32 v71, v71, v211, v151
	v_cvt_pk_bf16_f32 v234, v68, v69
	v_cvt_pk_bf16_f32 v235, v70, v71
	s_nop 0
	global_store_dwordx2 v243, v[234:235], s[20:21] offset:2048
	v_mul_f32_e32 v72, v72, v232
	v_mul_f32_e32 v73, v73, v232
	v_mul_f32_e32 v74, v74, v232
	v_mul_f32_e32 v75, v75, v232
	v_mul_f32_e32 v72, v136, v72
	v_mul_f32_e32 v73, v137, v73
	v_mul_f32_e32 v74, v138, v74
	v_mul_f32_e32 v75, v139, v75
	v_fma_f32 v72, v72, v212, v152
	v_fma_f32 v73, v73, v213, v153
	v_fma_f32 v74, v74, v214, v154
	v_fma_f32 v75, v75, v215, v155
	v_cvt_pk_bf16_f32 v234, v72, v73
	v_cvt_pk_bf16_f32 v235, v74, v75
	s_nop 0
	global_store_dwordx2 v243, v[234:235], s[22:23] offset:2048
	v_mul_f32_e32 v76, v76, v232
	v_mul_f32_e32 v77, v77, v232
	v_mul_f32_e32 v78, v78, v232
	v_mul_f32_e32 v79, v79, v232
	v_mul_f32_e32 v76, v140, v76
	v_mul_f32_e32 v77, v141, v77
	v_mul_f32_e32 v78, v142, v78
	v_mul_f32_e32 v79, v143, v79
	v_fma_f32 v76, v76, v216, v156
	v_fma_f32 v77, v77, v217, v157
	v_fma_f32 v78, v78, v218, v158
	v_fma_f32 v79, v79, v219, v159
	v_cvt_pk_bf16_f32 v234, v76, v77
	v_cvt_pk_bf16_f32 v235, v78, v79
	s_nop 0
	global_store_dwordx2 v243, v[234:235], s[24:25] offset:2048
	v_mul_f32_e32 v80, v80, v233
	v_mul_f32_e32 v81, v81, v233
	v_mul_f32_e32 v82, v82, v233
	v_mul_f32_e32 v83, v83, v233
	v_mul_f32_e32 v80, v128, v80
	v_mul_f32_e32 v81, v129, v81
	v_mul_f32_e32 v82, v130, v82
	v_mul_f32_e32 v83, v131, v83
	v_fma_f32 v80, v80, v204, v144
	v_fma_f32 v81, v81, v205, v145
	v_fma_f32 v82, v82, v206, v146
	v_fma_f32 v83, v83, v207, v147
	v_cvt_pk_bf16_f32 v234, v80, v81
	v_cvt_pk_bf16_f32 v235, v82, v83
	s_nop 0
	global_store_dwordx2 v244, v[234:235], s[18:19] offset:2048
	v_mul_f32_e32 v84, v84, v233
	v_mul_f32_e32 v85, v85, v233
	v_mul_f32_e32 v86, v86, v233
	v_mul_f32_e32 v87, v87, v233
	v_mul_f32_e32 v84, v132, v84
	v_mul_f32_e32 v85, v133, v85
	v_mul_f32_e32 v86, v134, v86
	v_mul_f32_e32 v87, v135, v87
	v_fma_f32 v84, v84, v208, v148
	v_fma_f32 v85, v85, v209, v149
	v_fma_f32 v86, v86, v210, v150
	v_fma_f32 v87, v87, v211, v151
	v_cvt_pk_bf16_f32 v234, v84, v85
	v_cvt_pk_bf16_f32 v235, v86, v87
	s_nop 0
	global_store_dwordx2 v244, v[234:235], s[20:21] offset:2048
	v_mul_f32_e32 v88, v88, v233
	v_mul_f32_e32 v89, v89, v233
	v_mul_f32_e32 v90, v90, v233
	v_mul_f32_e32 v91, v91, v233
	v_mul_f32_e32 v88, v136, v88
	v_mul_f32_e32 v89, v137, v89
	v_mul_f32_e32 v90, v138, v90
	v_mul_f32_e32 v91, v139, v91
	v_fma_f32 v88, v88, v212, v152
	v_fma_f32 v89, v89, v213, v153
	v_fma_f32 v90, v90, v214, v154
	v_fma_f32 v91, v91, v215, v155
	v_cvt_pk_bf16_f32 v234, v88, v89
	v_cvt_pk_bf16_f32 v235, v90, v91
	s_nop 0
	global_store_dwordx2 v244, v[234:235], s[22:23] offset:2048
	v_mul_f32_e32 v92, v92, v233
	v_mul_f32_e32 v93, v93, v233
	v_mul_f32_e32 v94, v94, v233
	v_mul_f32_e32 v95, v95, v233
	v_mul_f32_e32 v92, v140, v92
	v_mul_f32_e32 v93, v141, v93
	v_mul_f32_e32 v94, v142, v94
	v_mul_f32_e32 v95, v143, v95
	v_fma_f32 v92, v92, v216, v156
	v_fma_f32 v93, v93, v217, v157
	v_fma_f32 v94, v94, v218, v158
	v_fma_f32 v95, v95, v219, v159
	v_cvt_pk_bf16_f32 v234, v92, v93
	v_cvt_pk_bf16_f32 v235, v94, v95
	s_nop 0
	global_store_dwordx2 v244, v[234:235], s[24:25] offset:2048
	s_waitcnt vmcnt(24)
; DI unsigned pk2(float lo, float hi) { unsigned r; asm volatile("v_cvt_pk_bf16_f32 %0, %1, %2" : "=v"(r) : "v"(lo), "v"(hi)); return r; }
; DI float shx(float v, int m, int lane) { return __int_as_float(__builtin_amdgcn_ds_bpermute((lane ^ m) << 2, __float_as_int(v))); }
; DI void norm_rows(const Params& p, int layer, int row0, int nrows, int wstart, int wstride, int tid) {
;     ...
;     for (int i = 0; i < 4; ++i) { sa += va[i].x * va[i].x + va[i].y * va[i].y + va[i].z * va[i].z + va[i].w * va[i].w; sb += vb[i].x * vb[i].x + vb[i].y * vb[i].y + vb[i].z * vb[i].z + vb[i].w * vb[i].w; }
; #pragma unroll
;     for (int o = 32; o >= 1; o >>= 1) { sa += shx(sa, o, lane); sb += shx(sb, o, lane); }
; #pragma unroll
;     for (int rr = 0; rr < 2; ++rr) {
;       const int row = rr ? rowb : rowa; const float rinv = rsqrtf((rr ? sb : sa) * (1.0f / 1024.0f) + EPS);
;       if (layer < NLAYER) {
;         const int b = row >> 13; const float* md = modb + (size_t)(layer * 4 + b) * 3072; const float* g = p.norm_g + layer * 1024;
; #pragma unroll
;         for (int i = 0; i < 4; ++i) {
;           const float4 x4 = rr ? vb[i] : va[i];
;           const int e = i * 256 + lane * 4;
;           const float4 g4 = *(const float4*)(g + e), sh = *(const float4*)(md + e), sc = *(const float4*)(md + 1024 + e);
;           uint2 w;
;           w.x = pk2(x4.x * rinv * g4.x * (1.f + sc.x) + sh.x, x4.y * rinv * g4.y * (1.f + sc.y) + sh.y);
;           w.y = pk2(x4.z * rinv * g4.z * (1.f + sc.z) + sh.z, x4.w * rinv * g4.w * (1.f + sc.w) + sh.w);
;           *(uint2*)(h + wimg_off(row, e, DM)) = w;
	v_mul_f32_e32 v220, v97, v97
	v_mul_f32_e32 v224, v113, v113
	v_fmac_f32_e32 v220, v96, v96
	v_fmac_f32_e32 v224, v112, v112
	v_fmac_f32_e32 v220, v98, v98
	v_fmac_f32_e32 v224, v114, v114
	v_fmac_f32_e32 v220, v99, v99
	v_fmac_f32_e32 v224, v115, v115
	v_mul_f32_e32 v221, v101, v101
	v_mul_f32_e32 v225, v117, v117
	v_fmac_f32_e32 v221, v100, v100
	v_fmac_f32_e32 v225, v116, v116
	v_fmac_f32_e32 v221, v102, v102
	v_fmac_f32_e32 v225, v118, v118
	v_fmac_f32_e32 v221, v103, v103
	v_fmac_f32_e32 v225, v119, v119
	v_mul_f32_e32 v222, v105, v105
	v_mul_f32_e32 v226, v121, v121
	v_fmac_f32_e32 v222, v104, v104
	v_fmac_f32_e32 v226, v120, v120
	v_fmac_f32_e32 v222, v106, v106
	v_fmac_f32_e32 v226, v122, v122
	v_fmac_f32_e32 v222, v107, v107
	v_fmac_f32_e32 v226, v123, v123
	v_mul_f32_e32 v223, v109, v109
	v_mul_f32_e32 v227, v125, v125
	v_fmac_f32_e32 v223, v108, v108
	v_fmac_f32_e32 v227, v124, v124
	v_fmac_f32_e32 v223, v110, v110
	v_fmac_f32_e32 v227, v126, v126
	v_fmac_f32_e32 v223, v111, v111
	v_fmac_f32_e32 v227, v127, v127
	v_add_f32_e32 v228, v220, v221
	v_add_f32_e32 v229, v224, v225
	v_add_f32_e32 v228, v228, v222
	v_add_f32_e32 v229, v229, v226
	v_add_f32_e32 v228, v228, v223
	v_add_f32_e32 v229, v229, v227
	ds_bpermute_b32 v230, v236, v228
	ds_bpermute_b32 v231, v236, v229
	s_waitcnt lgkmcnt(0)
	v_add_f32_e32 v228, v228, v230
	v_add_f32_e32 v229, v229, v231
	ds_bpermute_b32 v230, v237, v228
	ds_bpermute_b32 v231, v237, v229
	s_waitcnt lgkmcnt(0)
	v_add_f32_e32 v228, v228, v230
	v_add_f32_e32 v229, v229, v231
	ds_bpermute_b32 v230, v238, v228
	ds_bpermute_b32 v231, v238, v229
	s_waitcnt lgkmcnt(0)
	v_add_f32_e32 v228, v228, v230
	v_add_f32_e32 v229, v229, v231
	ds_bpermute_b32 v230, v239, v228
	ds_bpermute_b32 v231, v239, v229
	s_waitcnt lgkmcnt(0)
	v_add_f32_e32 v228, v228, v230
	v_add_f32_e32 v229, v229, v231
	ds_bpermute_b32 v230, v240, v228
	ds_bpermute_b32 v231, v240, v229
	s_waitcnt lgkmcnt(0)
	v_add_f32_e32 v228, v228, v230
	v_add_f32_e32 v229, v229, v231
	ds_bpermute_b32 v230, v241, v228
	ds_bpermute_b32 v231, v241, v229
	s_waitcnt lgkmcnt(0)
	v_add_f32_e32 v228, v228, v230
	v_add_f32_e32 v229, v229, v231
	v_fma_f32 v228, v228, s26, v162
	v_fma_f32 v229, v229, s26, v162
	v_rsq_f32_e32 v232, v228
	v_rsq_f32_e32 v233, v229
	s_nop 0
	v_mul_f32_e32 v96, v96, v232
	v_mul_f32_e32 v97, v97, v232
	v_mul_f32_e32 v98, v98, v232
	v_mul_f32_e32 v99, v99, v232
	v_mul_f32_e32 v96, v128, v96
	v_mul_f32_e32 v97, v129, v97
	v_mul_f32_e32 v98, v130, v98
	v_mul_f32_e32 v99, v131, v99
	v_fma_f32 v96, v96, v204, v144
	v_fma_f32 v97, v97, v205, v145
	v_fma_f32 v98, v98, v206, v146
	v_fma_f32 v99, v99, v207, v147
	v_cvt_pk_bf16_f32 v234, v96, v97
	v_cvt_pk_bf16_f32 v235, v98, v99
	s_nop 0
	global_store_dwordx2 v243, v[234:235], s[18:19] offset:3072
	v_mul_f32_e32 v100, v100, v232
	v_mul_f32_e32 v101, v101, v232
	v_mul_f32_e32 v102, v102, v232
	v_mul_f32_e32 v103, v103, v232
	v_mul_f32_e32 v100, v132, v100
	v_mul_f32_e32 v101, v133, v101
	v_mul_f32_e32 v102, v134, v102
	v_mul_f32_e32 v103, v135, v103
	v_fma_f32 v100, v100, v208, v148
	v_fma_f32 v101, v101, v209, v149
	v_fma_f32 v102, v102, v210, v150
	v_fma_f32 v103, v103, v211, v151
	v_cvt_pk_bf16_f32 v234, v100, v101
	v_cvt_pk_bf16_f32 v235, v102, v103
	s_nop 0
	global_store_dwordx2 v243, v[234:235], s[20:21] offset:3072
	v_mul_f32_e32 v104, v104, v232
	v_mul_f32_e32 v105, v105, v232
	v_mul_f32_e32 v106, v106, v232
	v_mul_f32_e32 v107, v107, v232
	v_mul_f32_e32 v104, v136, v104
	v_mul_f32_e32 v105, v137, v105
	v_mul_f32_e32 v106, v138, v106
	v_mul_f32_e32 v107, v139, v107
	v_fma_f32 v104, v104, v212, v152
	v_fma_f32 v105, v105, v213, v153
	v_fma_f32 v106, v106, v214, v154
	v_fma_f32 v107, v107, v215, v155
	v_cvt_pk_bf16_f32 v234, v104, v105
	v_cvt_pk_bf16_f32 v235, v106, v107
	s_nop 0
	global_store_dwordx2 v243, v[234:235], s[22:23] offset:3072
	v_mul_f32_e32 v108, v108, v232
	v_mul_f32_e32 v109, v109, v232
	v_mul_f32_e32 v110, v110, v232
	v_mul_f32_e32 v111, v111, v232
	v_mul_f32_e32 v108, v140, v108
	v_mul_f32_e32 v109, v141, v109
	v_mul_f32_e32 v110, v142, v110
	v_mul_f32_e32 v111, v143, v111
	v_fma_f32 v108, v108, v216, v156
	v_fma_f32 v109, v109, v217, v157
	v_fma_f32 v110, v110, v218, v158
	v_fma_f32 v111, v111, v219, v159
	v_cvt_pk_bf16_f32 v234, v108, v109
	v_cvt_pk_bf16_f32 v235, v110, v111
	s_nop 0
	global_store_dwordx2 v243, v[234:235], s[24:25] offset:3072
	v_mul_f32_e32 v112, v112, v233
	v_mul_f32_e32 v113, v113, v233
	v_mul_f32_e32 v114, v114, v233
	v_mul_f32_e32 v115, v115, v233
	v_mul_f32_e32 v112, v128, v112
	v_mul_f32_e32 v113, v129, v113
	v_mul_f32_e32 v114, v130, v114
	v_mul_f32_e32 v115, v131, v115
	v_fma_f32 v112, v112, v204, v144
	v_fma_f32 v113, v113, v205, v145
	v_fma_f32 v114, v114, v206, v146
	v_fma_f32 v115, v115, v207, v147
	v_cvt_pk_bf16_f32 v234, v112, v113
	v_cvt_pk_bf16_f32 v235, v114, v115
	s_nop 0
	global_store_dwordx2 v244, v[234:235], s[18:19] offset:3072
	v_mul_f32_e32 v116, v116, v233
	v_mul_f32_e32 v117, v117, v233
	v_mul_f32_e32 v118, v118, v233
	v_mul_f32_e32 v119, v119, v233
	v_mul_f32_e32 v116, v132, v116
	v_mul_f32_e32 v117, v133, v117
	v_mul_f32_e32 v118, v134, v118
	v_mul_f32_e32 v119, v135, v119
	v_fma_f32 v116, v116, v208, v148
	v_fma_f32 v117, v117, v209, v149
	v_fma_f32 v118, v118, v210, v150
	v_fma_f32 v119, v119, v211, v151
	v_cvt_pk_bf16_f32 v234, v116, v117
	v_cvt_pk_bf16_f32 v235, v118, v119
	s_nop 0
	global_store_dwordx2 v244, v[234:235], s[20:21] offset:3072
	v_mul_f32_e32 v120, v120, v233
	v_mul_f32_e32 v121, v121, v233
	v_mul_f32_e32 v122, v122, v233
	v_mul_f32_e32 v123, v123, v233
	v_mul_f32_e32 v120, v136, v120
	v_mul_f32_e32 v121, v137, v121
; DI unsigned pk2(float lo, float hi) { unsigned r; asm volatile("v_cvt_pk_bf16_f32 %0, %1, %2" : "=v"(r) : "v"(lo), "v"(hi)); return r; }
; DI float shx(float v, int m, int lane) { return __int_as_float(__builtin_amdgcn_ds_bpermute((lane ^ m) << 2, __float_as_int(v))); }
; DI void norm_rows(const Params& p, int layer, int row0, int nrows, int wstart, int wstride, int tid) {
;     ...
;   for (int rowa = row0 + wstart + wid; rowa < row0 + nrows; rowa += 2 * wstride) {
;     const int rowb = (rowa + wstride < row0 + nrows) ? rowa + wstride : rowa;
;     float4 va[4], vb[4]; float sa = 0.f, sb = 0.f;
; #pragma unroll
;     for (int i = 0; i < 4; ++i) { va[i] = *(const float4*)(xin + (size_t)rowa * DM + i * 256 + lane * 4); vb[i] = *(const float4*)(xin + (size_t)rowb * DM + i * 256 + lane * 4); }
; #pragma unroll
;     for (int i = 0; i < 4; ++i) { sa += va[i].x * va[i].x + va[i].y * va[i].y + va[i].z * va[i].z + va[i].w * va[i].w; sb += vb[i].x * vb[i].x + vb[i].y * vb[i].y + vb[i].z * vb[i].z + vb[i].w * vb[i].w; }
; #pragma unroll
;     for (int o = 32; o >= 1; o >>= 1) { sa += shx(sa, o, lane); sb += shx(sb, o, lane); }
; #pragma unroll
;     for (int rr = 0; rr < 2; ++rr) {
;       const int row = rr ? rowb : rowa; const float rinv = rsqrtf((rr ? sb : sa) * (1.0f / 1024.0f) + EPS);
;       if (layer < NLAYER) {
;         const int b = row >> 13; const float* md = modb + (size_t)(layer * 4 + b) * 3072; const float* g = p.norm_g + layer * 1024;
; #pragma unroll
;         for (int i = 0; i < 4; ++i) {
;           const float4 x4 = rr ? vb[i] : va[i];
;           const int e = i * 256 + lane * 4;
;           const float4 g4 = *(const float4*)(g + e), sh = *(const float4*)(md + e), sc = *(const float4*)(md + 1024 + e);
;           uint2 w;
;           w.x = pk2(x4.x * rinv * g4.x * (1.f + sc.x) + sh.x, x4.y * rinv * g4.y * (1.f + sc.y) + sh.y);
;           w.y = pk2(x4.z * rinv * g4.z * (1.f + sc.z) + sh.z, x4.w * rinv * g4.w * (1.f + sc.w) + sh.w);
;           *(uint2*)(h + wimg_off(row, e, DM)) = w;
	v_mul_f32_e32 v122, v138, v122
	v_mul_f32_e32 v123, v139, v123
	v_fma_f32 v120, v120, v212, v152
	v_fma_f32 v121, v121, v213, v153
	v_fma_f32 v122, v122, v214, v154
	v_fma_f32 v123, v123, v215, v155
	v_cvt_pk_bf16_f32 v234, v120, v121
	v_cvt_pk_bf16_f32 v235, v122, v123
	s_nop 0
	global_store_dwordx2 v244, v[234:235], s[22:23] offset:3072
	v_mul_f32_e32 v124, v124, v233
	v_mul_f32_e32 v125, v125, v233
	v_mul_f32_e32 v126, v126, v233
	v_mul_f32_e32 v127, v127, v233
	v_mul_f32_e32 v124, v140, v124
	v_mul_f32_e32 v125, v141, v125
	v_mul_f32_e32 v126, v142, v126
	v_mul_f32_e32 v127, v143, v127
	v_fma_f32 v124, v124, v216, v156
	v_fma_f32 v125, v125, v217, v157
	v_fma_f32 v126, v126, v218, v158
	v_fma_f32 v127, v127, v219, v159
	v_cvt_pk_bf16_f32 v234, v124, v125
	v_cvt_pk_bf16_f32 v235, v126, v127
	s_nop 0
	global_store_dwordx2 v244, v[234:235], s[24:25] offset:3072
	v_readlane_b32 s0, v253, 47
	v_readlane_b32 s4, v252, 2
	v_readlane_b32 s5, v252, 3
	v_readlane_b32 s6, v252, 8
	v_readlane_b32 s7, v252, 9
	v_readlane_b32 s8, v252, 22
	v_readlane_b32 s9, v252, 23
	v_readlane_b32 s18, v252, 48
	v_readlane_b32 s19, v252, 49
	s_lshl_b32 s0, s0, 3
	s_add_i32 s0, s0, 0x4000
	s_lshl_b32 s1, s0, 12
	s_add_u32 s4, s4, s1
	s_addc_u32 s5, s5, 0
	s_add_u32 s6, s6, 0
	s_addc_u32 s7, s7, 0
	s_lshr_b32 s1, s0, 13
	s_mul_i32 s1, s1, 0x3000
	s_add_u32 s8, s8, s1
	s_addc_u32 s9, s9, 0
	s_add_u32 s10, s8, 0x1000
	s_addc_u32 s11, s9, 0
	s_lshr_b32 s1, s0, 7
	s_lshl_b32 s1, s1, 18
	s_bfe_u32 s12, s0, 0x10006
	s_lshl_b32 s12, s12, 12
	s_add_u32 s1, s1, s12
	s_add_u32 s18, s18, s1
	s_addc_u32 s19, s19, 0
	v_and_b32_e32 v245, 63, v163
	v_lshrrev_b32_e32 v246, 6, v163
	v_lshlrev_b32_e32 v247, 2, v245
	v_xor_b32_e32 v236, 0x80, v247
	v_xor_b32_e32 v237, 0x40, v247
	v_xor_b32_e32 v238, 0x20, v247
	v_xor_b32_e32 v239, 0x10, v247
	v_xor_b32_e32 v240, 0x8, v247
	v_xor_b32_e32 v241, 0x4, v247
	v_lshlrev_b32_e32 v245, 4, v245
	v_lshl_add_u32 v242, v246, 12, v245
	v_and_b32_e32 v248, 63, v163
	v_lshrrev_b32_e32 v249, 3, v248
	v_and_b32_e32 v248, 7, v248
	v_lshlrev_b32_e32 v248, 3, v248
	v_lshlrev_b32_e32 v249, 13, v249
	v_lshl_add_u32 v249, v246, 6, v249
	v_add_u32_e32 v243, v249, v248
	v_xor_b32_e32 v248, 32, v248
	v_add_u32_e32 v244, v249, v248
	v_add_u32_e32 v244, 0x200, v244
	global_load_dwordx4 v[128:131], v245, s[6:7] offset:0
	global_load_dwordx4 v[132:135], v245, s[6:7] offset:1024
	global_load_dwordx4 v[136:139], v245, s[6:7] offset:2048
	global_load_dwordx4 v[140:143], v245, s[6:7] offset:3072
	global_load_dwordx4 v[144:147], v245, s[8:9] offset:0
	global_load_dwordx4 v[148:151], v245, s[8:9] offset:1024
	global_load_dwordx4 v[152:155], v245, s[8:9] offset:2048
	global_load_dwordx4 v[156:159], v245, s[8:9] offset:3072
	global_load_dwordx4 v[204:207], v245, s[10:11] offset:0
	global_load_dwordx4 v[208:211], v245, s[10:11] offset:1024
	global_load_dwordx4 v[212:215], v245, s[10:11] offset:2048
	global_load_dwordx4 v[216:219], v245, s[10:11] offset:3072
	global_load_dwordx4 v[0:3], v242, s[4:5] offset:0
	global_load_dwordx4 v[4:7], v242, s[4:5] offset:1024
	global_load_dwordx4 v[8:11], v242, s[4:5] offset:2048
	global_load_dwordx4 v[12:15], v242, s[4:5] offset:3072
	s_add_u32 s4, s4, 0x8000
	s_addc_u32 s5, s5, 0
	global_load_dwordx4 v[16:19], v242, s[4:5] offset:0
	global_load_dwordx4 v[20:23], v242, s[4:5] offset:1024
	global_load_dwordx4 v[24:27], v242, s[4:5] offset:2048
	global_load_dwordx4 v[28:31], v242, s[4:5] offset:3072
	s_add_u32 s4, s4, 0x8000
	s_addc_u32 s5, s5, 0
	global_load_dwordx4 v[32:35], v242, s[4:5] offset:0
	global_load_dwordx4 v[36:39], v242, s[4:5] offset:1024
	global_load_dwordx4 v[40:43], v242, s[4:5] offset:2048
	global_load_dwordx4 v[44:47], v242, s[4:5] offset:3072
	s_add_u32 s4, s4, 0x8000
	s_addc_u32 s5, s5, 0
	global_load_dwordx4 v[48:51], v242, s[4:5] offset:0
	global_load_dwordx4 v[52:55], v242, s[4:5] offset:1024
	global_load_dwordx4 v[56:59], v242, s[4:5] offset:2048
	global_load_dwordx4 v[60:63], v242, s[4:5] offset:3072
	s_add_u32 s4, s4, 0x8000
	s_addc_u32 s5, s5, 0
	global_load_dwordx4 v[64:67], v242, s[4:5] offset:0
	global_load_dwordx4 v[68:71], v242, s[4:5] offset:1024
	global_load_dwordx4 v[72:75], v242, s[4:5] offset:2048
	global_load_dwordx4 v[76:79], v242, s[4:5] offset:3072
	s_add_u32 s4, s4, 0x8000
	s_addc_u32 s5, s5, 0
	global_load_dwordx4 v[80:83], v242, s[4:5] offset:0
	global_load_dwordx4 v[84:87], v242, s[4:5] offset:1024
	global_load_dwordx4 v[88:91], v242, s[4:5] offset:2048
	global_load_dwordx4 v[92:95], v242, s[4:5] offset:3072
	s_add_u32 s4, s4, 0x8000
	s_addc_u32 s5, s5, 0
	global_load_dwordx4 v[96:99], v242, s[4:5] offset:0
	global_load_dwordx4 v[100:103], v242, s[4:5] offset:1024
	global_load_dwordx4 v[104:107], v242, s[4:5] offset:2048
	global_load_dwordx4 v[108:111], v242, s[4:5] offset:3072
	s_add_u32 s4, s4, 0x8000
	s_addc_u32 s5, s5, 0
	global_load_dwordx4 v[112:115], v242, s[4:5] offset:0
	global_load_dwordx4 v[116:119], v242, s[4:5] offset:1024
	global_load_dwordx4 v[120:123], v242, s[4:5] offset:2048
	global_load_dwordx4 v[124:127], v242, s[4:5] offset:3072
	s_add_u32 s20, s18, 0x10000
	s_addc_u32 s21, s19, 0
	s_add_u32 s22, s18, 0x20000
	s_addc_u32 s23, s19, 0
	s_add_u32 s24, s18, 0x30000
	s_addc_u32 s25, s19, 0
	s_mov_b32 s26, 0x3a800000
	s_waitcnt vmcnt(24)
; DI unsigned pk2(float lo, float hi) { unsigned r; asm volatile("v_cvt_pk_bf16_f32 %0, %1, %2" : "=v"(r) : "v"(lo), "v"(hi)); return r; }
; DI float shx(float v, int m, int lane) { return __int_as_float(__builtin_amdgcn_ds_bpermute((lane ^ m) << 2, __float_as_int(v))); }
; DI void norm_rows(const Params& p, int layer, int row0, int nrows, int wstart, int wstride, int tid) {
;     ...
;     for (int i = 0; i < 4; ++i) { sa += va[i].x * va[i].x + va[i].y * va[i].y + va[i].z * va[i].z + va[i].w * va[i].w; sb += vb[i].x * vb[i].x + vb[i].y * vb[i].y + vb[i].z * vb[i].z + vb[i].w * vb[i].w; }
; #pragma unroll
;     for (int o = 32; o >= 1; o >>= 1) { sa += shx(sa, o, lane); sb += shx(sb, o, lane); }
; #pragma unroll
;     for (int rr = 0; rr < 2; ++rr) {
;       const int row = rr ? rowb : rowa; const float rinv = rsqrtf((rr ? sb : sa) * (1.0f / 1024.0f) + EPS);
;       if (layer < NLAYER) {
;         const int b = row >> 13; const float* md = modb + (size_t)(layer * 4 + b) * 3072; const float* g = p.norm_g + layer * 1024;
; #pragma unroll
;         for (int i = 0; i < 4; ++i) {
;           const float4 x4 = rr ? vb[i] : va[i];
;           const int e = i * 256 + lane * 4;
;           const float4 g4 = *(const float4*)(g + e), sh = *(const float4*)(md + e), sc = *(const float4*)(md + 1024 + e);
;           uint2 w;
;           w.x = pk2(x4.x * rinv * g4.x * (1.f + sc.x) + sh.x, x4.y * rinv * g4.y * (1.f + sc.y) + sh.y);
;           w.y = pk2(x4.z * rinv * g4.z * (1.f + sc.z) + sh.z, x4.w * rinv * g4.w * (1.f + sc.w) + sh.w);
;           *(uint2*)(h + wimg_off(row, e, DM)) = w;
	v_add_f32_e32 v204, 1.0, v204
	v_add_f32_e32 v205, 1.0, v205
	v_add_f32_e32 v206, 1.0, v206
	v_add_f32_e32 v207, 1.0, v207
	v_add_f32_e32 v208, 1.0, v208
	v_add_f32_e32 v209, 1.0, v209
	v_add_f32_e32 v210, 1.0, v210
	v_add_f32_e32 v211, 1.0, v211
	v_add_f32_e32 v212, 1.0, v212
	v_add_f32_e32 v213, 1.0, v213
	v_add_f32_e32 v214, 1.0, v214
	v_add_f32_e32 v215, 1.0, v215
	v_add_f32_e32 v216, 1.0, v216
	v_add_f32_e32 v217, 1.0, v217
	v_add_f32_e32 v218, 1.0, v218
	v_add_f32_e32 v219, 1.0, v219
	v_mul_f32_e32 v220, v1, v1
	v_mul_f32_e32 v224, v17, v17
	v_fmac_f32_e32 v220, v0, v0
	v_fmac_f32_e32 v224, v16, v16
	v_fmac_f32_e32 v220, v2, v2
	v_fmac_f32_e32 v224, v18, v18
	v_fmac_f32_e32 v220, v3, v3
	v_fmac_f32_e32 v224, v19, v19
	v_mul_f32_e32 v221, v5, v5
	v_mul_f32_e32 v225, v21, v21
	v_fmac_f32_e32 v221, v4, v4
	v_fmac_f32_e32 v225, v20, v20
	v_fmac_f32_e32 v221, v6, v6
	v_fmac_f32_e32 v225, v22, v22
	v_fmac_f32_e32 v221, v7, v7
	v_fmac_f32_e32 v225, v23, v23
	v_mul_f32_e32 v222, v9, v9
	v_mul_f32_e32 v226, v25, v25
	v_fmac_f32_e32 v222, v8, v8
	v_fmac_f32_e32 v226, v24, v24
	v_fmac_f32_e32 v222, v10, v10
	v_fmac_f32_e32 v226, v26, v26
	v_fmac_f32_e32 v222, v11, v11
	v_fmac_f32_e32 v226, v27, v27
	v_mul_f32_e32 v223, v13, v13
	v_mul_f32_e32 v227, v29, v29
	v_fmac_f32_e32 v223, v12, v12
	v_fmac_f32_e32 v227, v28, v28
	v_fmac_f32_e32 v223, v14, v14
	v_fmac_f32_e32 v227, v30, v30
	v_fmac_f32_e32 v223, v15, v15
	v_fmac_f32_e32 v227, v31, v31
	v_add_f32_e32 v228, v220, v221
	v_add_f32_e32 v229, v224, v225
	v_add_f32_e32 v228, v228, v222
	v_add_f32_e32 v229, v229, v226
	v_add_f32_e32 v228, v228, v223
	v_add_f32_e32 v229, v229, v227
	ds_bpermute_b32 v230, v236, v228
	ds_bpermute_b32 v231, v236, v229
	s_waitcnt lgkmcnt(0)
	v_add_f32_e32 v228, v228, v230
	v_add_f32_e32 v229, v229, v231
	ds_bpermute_b32 v230, v237, v228
	ds_bpermute_b32 v231, v237, v229
	s_waitcnt lgkmcnt(0)
	v_add_f32_e32 v228, v228, v230
	v_add_f32_e32 v229, v229, v231
	ds_bpermute_b32 v230, v238, v228
	ds_bpermute_b32 v231, v238, v229
	s_waitcnt lgkmcnt(0)
	v_add_f32_e32 v228, v228, v230
	v_add_f32_e32 v229, v229, v231
	ds_bpermute_b32 v230, v239, v228
	ds_bpermute_b32 v231, v239, v229
	s_waitcnt lgkmcnt(0)
	v_add_f32_e32 v228, v228, v230
	v_add_f32_e32 v229, v229, v231
	ds_bpermute_b32 v230, v240, v228
	ds_bpermute_b32 v231, v240, v229
	s_waitcnt lgkmcnt(0)
	v_add_f32_e32 v228, v228, v230
	v_add_f32_e32 v229, v229, v231
	ds_bpermute_b32 v230, v241, v228
	ds_bpermute_b32 v231, v241, v229
	s_waitcnt lgkmcnt(0)
	v_add_f32_e32 v228, v228, v230
	v_add_f32_e32 v229, v229, v231
	v_fma_f32 v228, v228, s26, v162
	v_fma_f32 v229, v229, s26, v162
	v_rsq_f32_e32 v232, v228
	v_rsq_f32_e32 v233, v229
	s_nop 0
	v_mul_f32_e32 v0, v0, v232
	v_mul_f32_e32 v1, v1, v232
	v_mul_f32_e32 v2, v2, v232
	v_mul_f32_e32 v3, v3, v232
	v_mul_f32_e32 v0, v128, v0
	v_mul_f32_e32 v1, v129, v1
	v_mul_f32_e32 v2, v130, v2
	v_mul_f32_e32 v3, v131, v3
	v_fma_f32 v0, v0, v204, v144
	v_fma_f32 v1, v1, v205, v145
	v_fma_f32 v2, v2, v206, v146
	v_fma_f32 v3, v3, v207, v147
	v_cvt_pk_bf16_f32 v234, v0, v1
	v_cvt_pk_bf16_f32 v235, v2, v3
	s_nop 0
	global_store_dwordx2 v243, v[234:235], s[18:19] offset:0
	v_mul_f32_e32 v4, v4, v232
	v_mul_f32_e32 v5, v5, v232
	v_mul_f32_e32 v6, v6, v232
	v_mul_f32_e32 v7, v7, v232
	v_mul_f32_e32 v4, v132, v4
	v_mul_f32_e32 v5, v133, v5
	v_mul_f32_e32 v6, v134, v6
	v_mul_f32_e32 v7, v135, v7
	v_fma_f32 v4, v4, v208, v148
	v_fma_f32 v5, v5, v209, v149
	v_fma_f32 v6, v6, v210, v150
	v_fma_f32 v7, v7, v211, v151
	v_cvt_pk_bf16_f32 v234, v4, v5
	v_cvt_pk_bf16_f32 v235, v6, v7
	s_nop 0
	global_store_dwordx2 v243, v[234:235], s[20:21] offset:0
	v_mul_f32_e32 v8, v8, v232
	v_mul_f32_e32 v9, v9, v232
	v_mul_f32_e32 v10, v10, v232
	v_mul_f32_e32 v11, v11, v232
	v_mul_f32_e32 v8, v136, v8
	v_mul_f32_e32 v9, v137, v9
	v_mul_f32_e32 v10, v138, v10
	v_mul_f32_e32 v11, v139, v11
	v_fma_f32 v8, v8, v212, v152
	v_fma_f32 v9, v9, v213, v153
	v_fma_f32 v10, v10, v214, v154
	v_fma_f32 v11, v11, v215, v155
	v_cvt_pk_bf16_f32 v234, v8, v9
	v_cvt_pk_bf16_f32 v235, v10, v11
	s_nop 0
	global_store_dwordx2 v243, v[234:235], s[22:23] offset:0
	v_mul_f32_e32 v12, v12, v232
	v_mul_f32_e32 v13, v13, v232
	v_mul_f32_e32 v14, v14, v232
	v_mul_f32_e32 v15, v15, v232
	v_mul_f32_e32 v12, v140, v12
	v_mul_f32_e32 v13, v141, v13
	v_mul_f32_e32 v14, v142, v14
	v_mul_f32_e32 v15, v143, v15
	v_fma_f32 v12, v12, v216, v156
	v_fma_f32 v13, v13, v217, v157
	v_fma_f32 v14, v14, v218, v158
	v_fma_f32 v15, v15, v219, v159
	v_cvt_pk_bf16_f32 v234, v12, v13
	v_cvt_pk_bf16_f32 v235, v14, v15
	s_nop 0
	global_store_dwordx2 v243, v[234:235], s[24:25] offset:0
	v_mul_f32_e32 v16, v16, v233
	v_mul_f32_e32 v17, v17, v233
	v_mul_f32_e32 v18, v18, v233
	v_mul_f32_e32 v19, v19, v233
	v_mul_f32_e32 v16, v128, v16
	v_mul_f32_e32 v17, v129, v17
	v_mul_f32_e32 v18, v130, v18
	v_mul_f32_e32 v19, v131, v19
	v_fma_f32 v16, v16, v204, v144
	v_fma_f32 v17, v17, v205, v145
	v_fma_f32 v18, v18, v206, v146
	v_fma_f32 v19, v19, v207, v147
	v_cvt_pk_bf16_f32 v234, v16, v17
	v_cvt_pk_bf16_f32 v235, v18, v19
	s_nop 0
	global_store_dwordx2 v244, v[234:235], s[18:19] offset:0
	v_mul_f32_e32 v20, v20, v233
	v_mul_f32_e32 v21, v21, v233
	v_mul_f32_e32 v22, v22, v233
	v_mul_f32_e32 v23, v23, v233
	v_mul_f32_e32 v20, v132, v20
	v_mul_f32_e32 v21, v133, v21
	v_mul_f32_e32 v22, v134, v22
	v_mul_f32_e32 v23, v135, v23
	v_fma_f32 v20, v20, v208, v148
	v_fma_f32 v21, v21, v209, v149
	v_fma_f32 v22, v22, v210, v150
	v_fma_f32 v23, v23, v211, v151
	v_cvt_pk_bf16_f32 v234, v20, v21
	v_cvt_pk_bf16_f32 v235, v22, v23
	s_nop 0
	global_store_dwordx2 v244, v[234:235], s[20:21] offset:0
	v_mul_f32_e32 v24, v24, v233
	v_mul_f32_e32 v25, v25, v233
	v_mul_f32_e32 v26, v26, v233
	v_mul_f32_e32 v27, v27, v233
	v_mul_f32_e32 v24, v136, v24
	v_mul_f32_e32 v25, v137, v25
	v_mul_f32_e32 v26, v138, v26
	v_mul_f32_e32 v27, v139, v27
	v_fma_f32 v24, v24, v212, v152
	v_fma_f32 v25, v25, v213, v153
	v_fma_f32 v26, v26, v214, v154
	v_fma_f32 v27, v27, v215, v155
	v_cvt_pk_bf16_f32 v234, v24, v25
	v_cvt_pk_bf16_f32 v235, v26, v27
	s_nop 0
	global_store_dwordx2 v244, v[234:235], s[22:23] offset:0
	v_mul_f32_e32 v28, v28, v233
	v_mul_f32_e32 v29, v29, v233
	v_mul_f32_e32 v30, v30, v233
	v_mul_f32_e32 v31, v31, v233
	v_mul_f32_e32 v28, v140, v28
	v_mul_f32_e32 v29, v141, v29
	v_mul_f32_e32 v30, v142, v30
	v_mul_f32_e32 v31, v143, v31
	v_fma_f32 v28, v28, v216, v156
	v_fma_f32 v29, v29, v217, v157
	v_fma_f32 v30, v30, v218, v158
	v_fma_f32 v31, v31, v219, v159
	v_cvt_pk_bf16_f32 v234, v28, v29
	v_cvt_pk_bf16_f32 v235, v30, v31
	s_nop 0
	global_store_dwordx2 v244, v[234:235], s[24:25] offset:0
	s_waitcnt vmcnt(24)
; DI unsigned pk2(float lo, float hi) { unsigned r; asm volatile("v_cvt_pk_bf16_f32 %0, %1, %2" : "=v"(r) : "v"(lo), "v"(hi)); return r; }
; DI float shx(float v, int m, int lane) { return __int_as_float(__builtin_amdgcn_ds_bpermute((lane ^ m) << 2, __float_as_int(v))); }
; DI void norm_rows(const Params& p, int layer, int row0, int nrows, int wstart, int wstride, int tid) {
;     ...
;     for (int i = 0; i < 4; ++i) { sa += va[i].x * va[i].x + va[i].y * va[i].y + va[i].z * va[i].z + va[i].w * va[i].w; sb += vb[i].x * vb[i].x + vb[i].y * vb[i].y + vb[i].z * vb[i].z + vb[i].w * vb[i].w; }
; #pragma unroll
;     for (int o = 32; o >= 1; o >>= 1) { sa += shx(sa, o, lane); sb += shx(sb, o, lane); }
; #pragma unroll
;     for (int rr = 0; rr < 2; ++rr) {
;       const int row = rr ? rowb : rowa; const float rinv = rsqrtf((rr ? sb : sa) * (1.0f / 1024.0f) + EPS);
;       if (layer < NLAYER) {
;         const int b = row >> 13; const float* md = modb + (size_t)(layer * 4 + b) * 3072; const float* g = p.norm_g + layer * 1024;
; #pragma unroll
;         for (int i = 0; i < 4; ++i) {
;           const float4 x4 = rr ? vb[i] : va[i];
;           const int e = i * 256 + lane * 4;
;           const float4 g4 = *(const float4*)(g + e), sh = *(const float4*)(md + e), sc = *(const float4*)(md + 1024 + e);
;           uint2 w;
;           w.x = pk2(x4.x * rinv * g4.x * (1.f + sc.x) + sh.x, x4.y * rinv * g4.y * (1.f + sc.y) + sh.y);
;           w.y = pk2(x4.z * rinv * g4.z * (1.f + sc.z) + sh.z, x4.w * rinv * g4.w * (1.f + sc.w) + sh.w);
;           *(uint2*)(h + wimg_off(row, e, DM)) = w;
	v_mul_f32_e32 v220, v33, v33
	v_mul_f32_e32 v224, v49, v49
	v_fmac_f32_e32 v220, v32, v32
	v_fmac_f32_e32 v224, v48, v48
	v_fmac_f32_e32 v220, v34, v34
	v_fmac_f32_e32 v224, v50, v50
	v_fmac_f32_e32 v220, v35, v35
	v_fmac_f32_e32 v224, v51, v51
	v_mul_f32_e32 v221, v37, v37
	v_mul_f32_e32 v225, v53, v53
	v_fmac_f32_e32 v221, v36, v36
	v_fmac_f32_e32 v225, v52, v52
	v_fmac_f32_e32 v221, v38, v38
	v_fmac_f32_e32 v225, v54, v54
	v_fmac_f32_e32 v221, v39, v39
	v_fmac_f32_e32 v225, v55, v55
	v_mul_f32_e32 v222, v41, v41
	v_mul_f32_e32 v226, v57, v57
	v_fmac_f32_e32 v222, v40, v40
	v_fmac_f32_e32 v226, v56, v56
	v_fmac_f32_e32 v222, v42, v42
	v_fmac_f32_e32 v226, v58, v58
	v_fmac_f32_e32 v222, v43, v43
	v_fmac_f32_e32 v226, v59, v59
	v_mul_f32_e32 v223, v45, v45
	v_mul_f32_e32 v227, v61, v61
	v_fmac_f32_e32 v223, v44, v44
	v_fmac_f32_e32 v227, v60, v60
	v_fmac_f32_e32 v223, v46, v46
	v_fmac_f32_e32 v227, v62, v62
	v_fmac_f32_e32 v223, v47, v47
	v_fmac_f32_e32 v227, v63, v63
	v_add_f32_e32 v228, v220, v221
	v_add_f32_e32 v229, v224, v225
	v_add_f32_e32 v228, v228, v222
	v_add_f32_e32 v229, v229, v226
	v_add_f32_e32 v228, v228, v223
	v_add_f32_e32 v229, v229, v227
	ds_bpermute_b32 v230, v236, v228
	ds_bpermute_b32 v231, v236, v229
	s_waitcnt lgkmcnt(0)
	v_add_f32_e32 v228, v228, v230
	v_add_f32_e32 v229, v229, v231
	ds_bpermute_b32 v230, v237, v228
	ds_bpermute_b32 v231, v237, v229
	s_waitcnt lgkmcnt(0)
	v_add_f32_e32 v228, v228, v230
	v_add_f32_e32 v229, v229, v231
	ds_bpermute_b32 v230, v238, v228
	ds_bpermute_b32 v231, v238, v229
	s_waitcnt lgkmcnt(0)
	v_add_f32_e32 v228, v228, v230
	v_add_f32_e32 v229, v229, v231
	ds_bpermute_b32 v230, v239, v228
	ds_bpermute_b32 v231, v239, v229
	s_waitcnt lgkmcnt(0)
	v_add_f32_e32 v228, v228, v230
	v_add_f32_e32 v229, v229, v231
	ds_bpermute_b32 v230, v240, v228
	ds_bpermute_b32 v231, v240, v229
	s_waitcnt lgkmcnt(0)
	v_add_f32_e32 v228, v228, v230
	v_add_f32_e32 v229, v229, v231
	ds_bpermute_b32 v230, v241, v228
	ds_bpermute_b32 v231, v241, v229
	s_waitcnt lgkmcnt(0)
	v_add_f32_e32 v228, v228, v230
	v_add_f32_e32 v229, v229, v231
	v_fma_f32 v228, v228, s26, v162
	v_fma_f32 v229, v229, s26, v162
	v_rsq_f32_e32 v232, v228
	v_rsq_f32_e32 v233, v229
	s_nop 0
	v_mul_f32_e32 v32, v32, v232
	v_mul_f32_e32 v33, v33, v232
	v_mul_f32_e32 v34, v34, v232
	v_mul_f32_e32 v35, v35, v232
	v_mul_f32_e32 v32, v128, v32
	v_mul_f32_e32 v33, v129, v33
	v_mul_f32_e32 v34, v130, v34
	v_mul_f32_e32 v35, v131, v35
	v_fma_f32 v32, v32, v204, v144
	v_fma_f32 v33, v33, v205, v145
	v_fma_f32 v34, v34, v206, v146
	v_fma_f32 v35, v35, v207, v147
	v_cvt_pk_bf16_f32 v234, v32, v33
	v_cvt_pk_bf16_f32 v235, v34, v35
	s_nop 0
	global_store_dwordx2 v243, v[234:235], s[18:19] offset:1024
	v_mul_f32_e32 v36, v36, v232
	v_mul_f32_e32 v37, v37, v232
	v_mul_f32_e32 v38, v38, v232
	v_mul_f32_e32 v39, v39, v232
	v_mul_f32_e32 v36, v132, v36
	v_mul_f32_e32 v37, v133, v37
	v_mul_f32_e32 v38, v134, v38
	v_mul_f32_e32 v39, v135, v39
	v_fma_f32 v36, v36, v208, v148
	v_fma_f32 v37, v37, v209, v149
	v_fma_f32 v38, v38, v210, v150
	v_fma_f32 v39, v39, v211, v151
	v_cvt_pk_bf16_f32 v234, v36, v37
	v_cvt_pk_bf16_f32 v235, v38, v39
	s_nop 0
	global_store_dwordx2 v243, v[234:235], s[20:21] offset:1024
	v_mul_f32_e32 v40, v40, v232
	v_mul_f32_e32 v41, v41, v232
	v_mul_f32_e32 v42, v42, v232
	v_mul_f32_e32 v43, v43, v232
	v_mul_f32_e32 v40, v136, v40
	v_mul_f32_e32 v41, v137, v41
	v_mul_f32_e32 v42, v138, v42
	v_mul_f32_e32 v43, v139, v43
	v_fma_f32 v40, v40, v212, v152
	v_fma_f32 v41, v41, v213, v153
	v_fma_f32 v42, v42, v214, v154
	v_fma_f32 v43, v43, v215, v155
	v_cvt_pk_bf16_f32 v234, v40, v41
	v_cvt_pk_bf16_f32 v235, v42, v43
	s_nop 0
	global_store_dwordx2 v243, v[234:235], s[22:23] offset:1024
	v_mul_f32_e32 v44, v44, v232
	v_mul_f32_e32 v45, v45, v232
	v_mul_f32_e32 v46, v46, v232
	v_mul_f32_e32 v47, v47, v232
	v_mul_f32_e32 v44, v140, v44
	v_mul_f32_e32 v45, v141, v45
	v_mul_f32_e32 v46, v142, v46
	v_mul_f32_e32 v47, v143, v47
	v_fma_f32 v44, v44, v216, v156
	v_fma_f32 v45, v45, v217, v157
	v_fma_f32 v46, v46, v218, v158
	v_fma_f32 v47, v47, v219, v159
	v_cvt_pk_bf16_f32 v234, v44, v45
	v_cvt_pk_bf16_f32 v235, v46, v47
	s_nop 0
	global_store_dwordx2 v243, v[234:235], s[24:25] offset:1024
	v_mul_f32_e32 v48, v48, v233
	v_mul_f32_e32 v49, v49, v233
	v_mul_f32_e32 v50, v50, v233
	v_mul_f32_e32 v51, v51, v233
	v_mul_f32_e32 v48, v128, v48
	v_mul_f32_e32 v49, v129, v49
	v_mul_f32_e32 v50, v130, v50
	v_mul_f32_e32 v51, v131, v51
	v_fma_f32 v48, v48, v204, v144
	v_fma_f32 v49, v49, v205, v145
	v_fma_f32 v50, v50, v206, v146
	v_fma_f32 v51, v51, v207, v147
	v_cvt_pk_bf16_f32 v234, v48, v49
	v_cvt_pk_bf16_f32 v235, v50, v51
	s_nop 0
	global_store_dwordx2 v244, v[234:235], s[18:19] offset:1024
	v_mul_f32_e32 v52, v52, v233
	v_mul_f32_e32 v53, v53, v233
	v_mul_f32_e32 v54, v54, v233
	v_mul_f32_e32 v55, v55, v233
	v_mul_f32_e32 v52, v132, v52
	v_mul_f32_e32 v53, v133, v53
	v_mul_f32_e32 v54, v134, v54
	v_mul_f32_e32 v55, v135, v55
	v_fma_f32 v52, v52, v208, v148
	v_fma_f32 v53, v53, v209, v149
	v_fma_f32 v54, v54, v210, v150
	v_fma_f32 v55, v55, v211, v151
	v_cvt_pk_bf16_f32 v234, v52, v53
	v_cvt_pk_bf16_f32 v235, v54, v55
	s_nop 0
	global_store_dwordx2 v244, v[234:235], s[20:21] offset:1024
	v_mul_f32_e32 v56, v56, v233
	v_mul_f32_e32 v57, v57, v233
	v_mul_f32_e32 v58, v58, v233
	v_mul_f32_e32 v59, v59, v233
	v_mul_f32_e32 v56, v136, v56
	v_mul_f32_e32 v57, v137, v57
	v_mul_f32_e32 v58, v138, v58
	v_mul_f32_e32 v59, v139, v59
	v_fma_f32 v56, v56, v212, v152
	v_fma_f32 v57, v57, v213, v153
	v_fma_f32 v58, v58, v214, v154
	v_fma_f32 v59, v59, v215, v155
	v_cvt_pk_bf16_f32 v234, v56, v57
	v_cvt_pk_bf16_f32 v235, v58, v59
	s_nop 0
	global_store_dwordx2 v244, v[234:235], s[22:23] offset:1024
	v_mul_f32_e32 v60, v60, v233
	v_mul_f32_e32 v61, v61, v233
	v_mul_f32_e32 v62, v62, v233
	v_mul_f32_e32 v63, v63, v233
	v_mul_f32_e32 v60, v140, v60
	v_mul_f32_e32 v61, v141, v61
	v_mul_f32_e32 v62, v142, v62
	v_mul_f32_e32 v63, v143, v63
	v_fma_f32 v60, v60, v216, v156
	v_fma_f32 v61, v61, v217, v157
	v_fma_f32 v62, v62, v218, v158
	v_fma_f32 v63, v63, v219, v159
	v_cvt_pk_bf16_f32 v234, v60, v61
	v_cvt_pk_bf16_f32 v235, v62, v63
	s_nop 0
	global_store_dwordx2 v244, v[234:235], s[24:25] offset:1024
	s_waitcnt vmcnt(24)
; DI unsigned pk2(float lo, float hi) { unsigned r; asm volatile("v_cvt_pk_bf16_f32 %0, %1, %2" : "=v"(r) : "v"(lo), "v"(hi)); return r; }
; DI float shx(float v, int m, int lane) { return __int_as_float(__builtin_amdgcn_ds_bpermute((lane ^ m) << 2, __float_as_int(v))); }
; DI void norm_rows(const Params& p, int layer, int row0, int nrows, int wstart, int wstride, int tid) {
;     ...
;     for (int i = 0; i < 4; ++i) { sa += va[i].x * va[i].x + va[i].y * va[i].y + va[i].z * va[i].z + va[i].w * va[i].w; sb += vb[i].x * vb[i].x + vb[i].y * vb[i].y + vb[i].z * vb[i].z + vb[i].w * vb[i].w; }
; #pragma unroll
;     for (int o = 32; o >= 1; o >>= 1) { sa += shx(sa, o, lane); sb += shx(sb, o, lane); }
; #pragma unroll
;     for (int rr = 0; rr < 2; ++rr) {
;       const int row = rr ? rowb : rowa; const float rinv = rsqrtf((rr ? sb : sa) * (1.0f / 1024.0f) + EPS);
;       if (layer < NLAYER) {
;         const int b = row >> 13; const float* md = modb + (size_t)(layer * 4 + b) * 3072; const float* g = p.norm_g + layer * 1024;
; #pragma unroll
;         for (int i = 0; i < 4; ++i) {
;           const float4 x4 = rr ? vb[i] : va[i];
;           const int e = i * 256 + lane * 4;
;           const float4 g4 = *(const float4*)(g + e), sh = *(const float4*)(md + e), sc = *(const float4*)(md + 1024 + e);
;           uint2 w;
;           w.x = pk2(x4.x * rinv * g4.x * (1.f + sc.x) + sh.x, x4.y * rinv * g4.y * (1.f + sc.y) + sh.y);
;           w.y = pk2(x4.z * rinv * g4.z * (1.f + sc.z) + sh.z, x4.w * rinv * g4.w * (1.f + sc.w) + sh.w);
;           *(uint2*)(h + wimg_off(row, e, DM)) = w;
	v_mul_f32_e32 v220, v65, v65
	v_mul_f32_e32 v224, v81, v81
	v_fmac_f32_e32 v220, v64, v64
	v_fmac_f32_e32 v224, v80, v80
	v_fmac_f32_e32 v220, v66, v66
	v_fmac_f32_e32 v224, v82, v82
	v_fmac_f32_e32 v220, v67, v67
	v_fmac_f32_e32 v224, v83, v83
	v_mul_f32_e32 v221, v69, v69
	v_mul_f32_e32 v225, v85, v85
	v_fmac_f32_e32 v221, v68, v68
	v_fmac_f32_e32 v225, v84, v84
	v_fmac_f32_e32 v221, v70, v70
	v_fmac_f32_e32 v225, v86, v86
	v_fmac_f32_e32 v221, v71, v71
	v_fmac_f32_e32 v225, v87, v87
	v_mul_f32_e32 v222, v73, v73
	v_mul_f32_e32 v226, v89, v89
	v_fmac_f32_e32 v222, v72, v72
	v_fmac_f32_e32 v226, v88, v88
	v_fmac_f32_e32 v222, v74, v74
	v_fmac_f32_e32 v226, v90, v90
	v_fmac_f32_e32 v222, v75, v75
	v_fmac_f32_e32 v226, v91, v91
	v_mul_f32_e32 v223, v77, v77
	v_mul_f32_e32 v227, v93, v93
	v_fmac_f32_e32 v223, v76, v76
	v_fmac_f32_e32 v227, v92, v92
	v_fmac_f32_e32 v223, v78, v78
	v_fmac_f32_e32 v227, v94, v94
	v_fmac_f32_e32 v223, v79, v79
	v_fmac_f32_e32 v227, v95, v95
	v_add_f32_e32 v228, v220, v221
	v_add_f32_e32 v229, v224, v225
	v_add_f32_e32 v228, v228, v222
	v_add_f32_e32 v229, v229, v226
	v_add_f32_e32 v228, v228, v223
	v_add_f32_e32 v229, v229, v227
	ds_bpermute_b32 v230, v236, v228
	ds_bpermute_b32 v231, v236, v229
	s_waitcnt lgkmcnt(0)
	v_add_f32_e32 v228, v228, v230
	v_add_f32_e32 v229, v229, v231
	ds_bpermute_b32 v230, v237, v228
	ds_bpermute_b32 v231, v237, v229
	s_waitcnt lgkmcnt(0)
	v_add_f32_e32 v228, v228, v230
	v_add_f32_e32 v229, v229, v231
	ds_bpermute_b32 v230, v238, v228
	ds_bpermute_b32 v231, v238, v229
	s_waitcnt lgkmcnt(0)
	v_add_f32_e32 v228, v228, v230
	v_add_f32_e32 v229, v229, v231
	ds_bpermute_b32 v230, v239, v228
	ds_bpermute_b32 v231, v239, v229
	s_waitcnt lgkmcnt(0)
	v_add_f32_e32 v228, v228, v230
	v_add_f32_e32 v229, v229, v231
	ds_bpermute_b32 v230, v240, v228
	ds_bpermute_b32 v231, v240, v229
	s_waitcnt lgkmcnt(0)
	v_add_f32_e32 v228, v228, v230
	v_add_f32_e32 v229, v229, v231
	ds_bpermute_b32 v230, v241, v228
	ds_bpermute_b32 v231, v241, v229
	s_waitcnt lgkmcnt(0)
	v_add_f32_e32 v228, v228, v230
	v_add_f32_e32 v229, v229, v231
	v_fma_f32 v228, v228, s26, v162
	v_fma_f32 v229, v229, s26, v162
	v_rsq_f32_e32 v232, v228
	v_rsq_f32_e32 v233, v229
	s_nop 0
	v_mul_f32_e32 v64, v64, v232
	v_mul_f32_e32 v65, v65, v232
	v_mul_f32_e32 v66, v66, v232
	v_mul_f32_e32 v67, v67, v232
	v_mul_f32_e32 v64, v128, v64
	v_mul_f32_e32 v65, v129, v65
	v_mul_f32_e32 v66, v130, v66
	v_mul_f32_e32 v67, v131, v67
	v_fma_f32 v64, v64, v204, v144
	v_fma_f32 v65, v65, v205, v145
	v_fma_f32 v66, v66, v206, v146
	v_fma_f32 v67, v67, v207, v147
	v_cvt_pk_bf16_f32 v234, v64, v65
	v_cvt_pk_bf16_f32 v235, v66, v67
	s_nop 0
	global_store_dwordx2 v243, v[234:235], s[18:19] offset:2048
	v_mul_f32_e32 v68, v68, v232
	v_mul_f32_e32 v69, v69, v232
	v_mul_f32_e32 v70, v70, v232
	v_mul_f32_e32 v71, v71, v232
	v_mul_f32_e32 v68, v132, v68
	v_mul_f32_e32 v69, v133, v69
	v_mul_f32_e32 v70, v134, v70
	v_mul_f32_e32 v71, v135, v71
	v_fma_f32 v68, v68, v208, v148
	v_fma_f32 v69, v69, v209, v149
	v_fma_f32 v70, v70, v210, v150
	v_fma_f32 v71, v71, v211, v151
	v_cvt_pk_bf16_f32 v234, v68, v69
	v_cvt_pk_bf16_f32 v235, v70, v71
	s_nop 0
	global_store_dwordx2 v243, v[234:235], s[20:21] offset:2048
	v_mul_f32_e32 v72, v72, v232
	v_mul_f32_e32 v73, v73, v232
	v_mul_f32_e32 v74, v74, v232
	v_mul_f32_e32 v75, v75, v232
	v_mul_f32_e32 v72, v136, v72
	v_mul_f32_e32 v73, v137, v73
	v_mul_f32_e32 v74, v138, v74
	v_mul_f32_e32 v75, v139, v75
	v_fma_f32 v72, v72, v212, v152
	v_fma_f32 v73, v73, v213, v153
	v_fma_f32 v74, v74, v214, v154
	v_fma_f32 v75, v75, v215, v155
	v_cvt_pk_bf16_f32 v234, v72, v73
	v_cvt_pk_bf16_f32 v235, v74, v75
	s_nop 0
	global_store_dwordx2 v243, v[234:235], s[22:23] offset:2048
	v_mul_f32_e32 v76, v76, v232
	v_mul_f32_e32 v77, v77, v232
	v_mul_f32_e32 v78, v78, v232
	v_mul_f32_e32 v79, v79, v232
	v_mul_f32_e32 v76, v140, v76
	v_mul_f32_e32 v77, v141, v77
	v_mul_f32_e32 v78, v142, v78
	v_mul_f32_e32 v79, v143, v79
	v_fma_f32 v76, v76, v216, v156
	v_fma_f32 v77, v77, v217, v157
	v_fma_f32 v78, v78, v218, v158
	v_fma_f32 v79, v79, v219, v159
	v_cvt_pk_bf16_f32 v234, v76, v77
	v_cvt_pk_bf16_f32 v235, v78, v79
	s_nop 0
	global_store_dwordx2 v243, v[234:235], s[24:25] offset:2048
	v_mul_f32_e32 v80, v80, v233
	v_mul_f32_e32 v81, v81, v233
	v_mul_f32_e32 v82, v82, v233
	v_mul_f32_e32 v83, v83, v233
	v_mul_f32_e32 v80, v128, v80
	v_mul_f32_e32 v81, v129, v81
	v_mul_f32_e32 v82, v130, v82
	v_mul_f32_e32 v83, v131, v83
	v_fma_f32 v80, v80, v204, v144
	v_fma_f32 v81, v81, v205, v145
	v_fma_f32 v82, v82, v206, v146
	v_fma_f32 v83, v83, v207, v147
	v_cvt_pk_bf16_f32 v234, v80, v81
	v_cvt_pk_bf16_f32 v235, v82, v83
	s_nop 0
	global_store_dwordx2 v244, v[234:235], s[18:19] offset:2048
	v_mul_f32_e32 v84, v84, v233
	v_mul_f32_e32 v85, v85, v233
	v_mul_f32_e32 v86, v86, v233
	v_mul_f32_e32 v87, v87, v233
	v_mul_f32_e32 v84, v132, v84
	v_mul_f32_e32 v85, v133, v85
	v_mul_f32_e32 v86, v134, v86
	v_mul_f32_e32 v87, v135, v87
	v_fma_f32 v84, v84, v208, v148
	v_fma_f32 v85, v85, v209, v149
	v_fma_f32 v86, v86, v210, v150
	v_fma_f32 v87, v87, v211, v151
	v_cvt_pk_bf16_f32 v234, v84, v85
	v_cvt_pk_bf16_f32 v235, v86, v87
	s_nop 0
	global_store_dwordx2 v244, v[234:235], s[20:21] offset:2048
	v_mul_f32_e32 v88, v88, v233
	v_mul_f32_e32 v89, v89, v233
	v_mul_f32_e32 v90, v90, v233
	v_mul_f32_e32 v91, v91, v233
	v_mul_f32_e32 v88, v136, v88
	v_mul_f32_e32 v89, v137, v89
	v_mul_f32_e32 v90, v138, v90
	v_mul_f32_e32 v91, v139, v91
	v_fma_f32 v88, v88, v212, v152
	v_fma_f32 v89, v89, v213, v153
	v_fma_f32 v90, v90, v214, v154
	v_fma_f32 v91, v91, v215, v155
	v_cvt_pk_bf16_f32 v234, v88, v89
	v_cvt_pk_bf16_f32 v235, v90, v91
	s_nop 0
	global_store_dwordx2 v244, v[234:235], s[22:23] offset:2048
	v_mul_f32_e32 v92, v92, v233
	v_mul_f32_e32 v93, v93, v233
	v_mul_f32_e32 v94, v94, v233
	v_mul_f32_e32 v95, v95, v233
	v_mul_f32_e32 v92, v140, v92
	v_mul_f32_e32 v93, v141, v93
	v_mul_f32_e32 v94, v142, v94
	v_mul_f32_e32 v95, v143, v95
	v_fma_f32 v92, v92, v216, v156
	v_fma_f32 v93, v93, v217, v157
	v_fma_f32 v94, v94, v218, v158
	v_fma_f32 v95, v95, v219, v159
	v_cvt_pk_bf16_f32 v234, v92, v93
	v_cvt_pk_bf16_f32 v235, v94, v95
	s_nop 0
	global_store_dwordx2 v244, v[234:235], s[24:25] offset:2048
	s_waitcnt vmcnt(24)
; DI unsigned pk2(float lo, float hi) { unsigned r; asm volatile("v_cvt_pk_bf16_f32 %0, %1, %2" : "=v"(r) : "v"(lo), "v"(hi)); return r; }
; DI float shx(float v, int m, int lane) { return __int_as_float(__builtin_amdgcn_ds_bpermute((lane ^ m) << 2, __float_as_int(v))); }
; DI void norm_rows(const Params& p, int layer, int row0, int nrows, int wstart, int wstride, int tid) {
;     ...
;     for (int i = 0; i < 4; ++i) { sa += va[i].x * va[i].x + va[i].y * va[i].y + va[i].z * va[i].z + va[i].w * va[i].w; sb += vb[i].x * vb[i].x + vb[i].y * vb[i].y + vb[i].z * vb[i].z + vb[i].w * vb[i].w; }
; #pragma unroll
;     for (int o = 32; o >= 1; o >>= 1) { sa += shx(sa, o, lane); sb += shx(sb, o, lane); }
; #pragma unroll
;     for (int rr = 0; rr < 2; ++rr) {
;       const int row = rr ? rowb : rowa; const float rinv = rsqrtf((rr ? sb : sa) * (1.0f / 1024.0f) + EPS);
;       if (layer < NLAYER) {
;         const int b = row >> 13; const float* md = modb + (size_t)(layer * 4 + b) * 3072; const float* g = p.norm_g + layer * 1024;
; #pragma unroll
;         for (int i = 0; i < 4; ++i) {
;           const float4 x4 = rr ? vb[i] : va[i];
;           const int e = i * 256 + lane * 4;
;           const float4 g4 = *(const float4*)(g + e), sh = *(const float4*)(md + e), sc = *(const float4*)(md + 1024 + e);
;           uint2 w;
;           w.x = pk2(x4.x * rinv * g4.x * (1.f + sc.x) + sh.x, x4.y * rinv * g4.y * (1.f + sc.y) + sh.y);
;           w.y = pk2(x4.z * rinv * g4.z * (1.f + sc.z) + sh.z, x4.w * rinv * g4.w * (1.f + sc.w) + sh.w);
;           *(uint2*)(h + wimg_off(row, e, DM)) = w;
	v_mul_f32_e32 v220, v97, v97
	v_mul_f32_e32 v224, v113, v113
	v_fmac_f32_e32 v220, v96, v96
	v_fmac_f32_e32 v224, v112, v112
	v_fmac_f32_e32 v220, v98, v98
	v_fmac_f32_e32 v224, v114, v114
	v_fmac_f32_e32 v220, v99, v99
	v_fmac_f32_e32 v224, v115, v115
	v_mul_f32_e32 v221, v101, v101
	v_mul_f32_e32 v225, v117, v117
	v_fmac_f32_e32 v221, v100, v100
	v_fmac_f32_e32 v225, v116, v116
	v_fmac_f32_e32 v221, v102, v102
	v_fmac_f32_e32 v225, v118, v118
	v_fmac_f32_e32 v221, v103, v103
	v_fmac_f32_e32 v225, v119, v119
	v_mul_f32_e32 v222, v105, v105
	v_mul_f32_e32 v226, v121, v121
	v_fmac_f32_e32 v222, v104, v104
	v_fmac_f32_e32 v226, v120, v120
	v_fmac_f32_e32 v222, v106, v106
	v_fmac_f32_e32 v226, v122, v122
	v_fmac_f32_e32 v222, v107, v107
	v_fmac_f32_e32 v226, v123, v123
	v_mul_f32_e32 v223, v109, v109
	v_mul_f32_e32 v227, v125, v125
	v_fmac_f32_e32 v223, v108, v108
	v_fmac_f32_e32 v227, v124, v124
	v_fmac_f32_e32 v223, v110, v110
	v_fmac_f32_e32 v227, v126, v126
	v_fmac_f32_e32 v223, v111, v111
	v_fmac_f32_e32 v227, v127, v127
	v_add_f32_e32 v228, v220, v221
	v_add_f32_e32 v229, v224, v225
	v_add_f32_e32 v228, v228, v222
	v_add_f32_e32 v229, v229, v226
	v_add_f32_e32 v228, v228, v223
	v_add_f32_e32 v229, v229, v227
	ds_bpermute_b32 v230, v236, v228
	ds_bpermute_b32 v231, v236, v229
	s_waitcnt lgkmcnt(0)
	v_add_f32_e32 v228, v228, v230
	v_add_f32_e32 v229, v229, v231
	ds_bpermute_b32 v230, v237, v228
	ds_bpermute_b32 v231, v237, v229
	s_waitcnt lgkmcnt(0)
	v_add_f32_e32 v228, v228, v230
	v_add_f32_e32 v229, v229, v231
	ds_bpermute_b32 v230, v238, v228
	ds_bpermute_b32 v231, v238, v229
	s_waitcnt lgkmcnt(0)
	v_add_f32_e32 v228, v228, v230
	v_add_f32_e32 v229, v229, v231
	ds_bpermute_b32 v230, v239, v228
	ds_bpermute_b32 v231, v239, v229
	s_waitcnt lgkmcnt(0)
	v_add_f32_e32 v228, v228, v230
	v_add_f32_e32 v229, v229, v231
	ds_bpermute_b32 v230, v240, v228
	ds_bpermute_b32 v231, v240, v229
	s_waitcnt lgkmcnt(0)
	v_add_f32_e32 v228, v228, v230
	v_add_f32_e32 v229, v229, v231
	ds_bpermute_b32 v230, v241, v228
	ds_bpermute_b32 v231, v241, v229
	s_waitcnt lgkmcnt(0)
	v_add_f32_e32 v228, v228, v230
	v_add_f32_e32 v229, v229, v231
	v_fma_f32 v228, v228, s26, v162
	v_fma_f32 v229, v229, s26, v162
	v_rsq_f32_e32 v232, v228
	v_rsq_f32_e32 v233, v229
	s_nop 0
	v_mul_f32_e32 v96, v96, v232
	v_mul_f32_e32 v97, v97, v232
	v_mul_f32_e32 v98, v98, v232
	v_mul_f32_e32 v99, v99, v232
	v_mul_f32_e32 v96, v128, v96
	v_mul_f32_e32 v97, v129, v97
	v_mul_f32_e32 v98, v130, v98
	v_mul_f32_e32 v99, v131, v99
	v_fma_f32 v96, v96, v204, v144
	v_fma_f32 v97, v97, v205, v145
	v_fma_f32 v98, v98, v206, v146
	v_fma_f32 v99, v99, v207, v147
	v_cvt_pk_bf16_f32 v234, v96, v97
	v_cvt_pk_bf16_f32 v235, v98, v99
	s_nop 0
	global_store_dwordx2 v243, v[234:235], s[18:19] offset:3072
	v_mul_f32_e32 v100, v100, v232
	v_mul_f32_e32 v101, v101, v232
	v_mul_f32_e32 v102, v102, v232
	v_mul_f32_e32 v103, v103, v232
	v_mul_f32_e32 v100, v132, v100
	v_mul_f32_e32 v101, v133, v101
	v_mul_f32_e32 v102, v134, v102
	v_mul_f32_e32 v103, v135, v103
	v_fma_f32 v100, v100, v208, v148
	v_fma_f32 v101, v101, v209, v149
	v_fma_f32 v102, v102, v210, v150
	v_fma_f32 v103, v103, v211, v151
	v_cvt_pk_bf16_f32 v234, v100, v101
	v_cvt_pk_bf16_f32 v235, v102, v103
	s_nop 0
	global_store_dwordx2 v243, v[234:235], s[20:21] offset:3072
	v_mul_f32_e32 v104, v104, v232
	v_mul_f32_e32 v105, v105, v232
	v_mul_f32_e32 v106, v106, v232
	v_mul_f32_e32 v107, v107, v232
	v_mul_f32_e32 v104, v136, v104
	v_mul_f32_e32 v105, v137, v105
	v_mul_f32_e32 v106, v138, v106
	v_mul_f32_e32 v107, v139, v107
	v_fma_f32 v104, v104, v212, v152
	v_fma_f32 v105, v105, v213, v153
	v_fma_f32 v106, v106, v214, v154
	v_fma_f32 v107, v107, v215, v155
	v_cvt_pk_bf16_f32 v234, v104, v105
	v_cvt_pk_bf16_f32 v235, v106, v107
	s_nop 0
	global_store_dwordx2 v243, v[234:235], s[22:23] offset:3072
	v_mul_f32_e32 v108, v108, v232
	v_mul_f32_e32 v109, v109, v232
	v_mul_f32_e32 v110, v110, v232
	v_mul_f32_e32 v111, v111, v232
	v_mul_f32_e32 v108, v140, v108
	v_mul_f32_e32 v109, v141, v109
	v_mul_f32_e32 v110, v142, v110
	v_mul_f32_e32 v111, v143, v111
	v_fma_f32 v108, v108, v216, v156
	v_fma_f32 v109, v109, v217, v157
	v_fma_f32 v110, v110, v218, v158
	v_fma_f32 v111, v111, v219, v159
	v_cvt_pk_bf16_f32 v234, v108, v109
	v_cvt_pk_bf16_f32 v235, v110, v111
	s_nop 0
	global_store_dwordx2 v243, v[234:235], s[24:25] offset:3072
	v_mul_f32_e32 v112, v112, v233
	v_mul_f32_e32 v113, v113, v233
	v_mul_f32_e32 v114, v114, v233
	v_mul_f32_e32 v115, v115, v233
	v_mul_f32_e32 v112, v128, v112
	v_mul_f32_e32 v113, v129, v113
	v_mul_f32_e32 v114, v130, v114
	v_mul_f32_e32 v115, v131, v115
	v_fma_f32 v112, v112, v204, v144
	v_fma_f32 v113, v113, v205, v145
	v_fma_f32 v114, v114, v206, v146
	v_fma_f32 v115, v115, v207, v147
	v_cvt_pk_bf16_f32 v234, v112, v113
	v_cvt_pk_bf16_f32 v235, v114, v115
	s_nop 0
	global_store_dwordx2 v244, v[234:235], s[18:19] offset:3072
	v_mul_f32_e32 v116, v116, v233
	v_mul_f32_e32 v117, v117, v233
	v_mul_f32_e32 v118, v118, v233
	v_mul_f32_e32 v119, v119, v233
	v_mul_f32_e32 v116, v132, v116
	v_mul_f32_e32 v117, v133, v117
	v_mul_f32_e32 v118, v134, v118
	v_mul_f32_e32 v119, v135, v119
	v_fma_f32 v116, v116, v208, v148
	v_fma_f32 v117, v117, v209, v149
	v_fma_f32 v118, v118, v210, v150
	v_fma_f32 v119, v119, v211, v151
	v_cvt_pk_bf16_f32 v234, v116, v117
	v_cvt_pk_bf16_f32 v235, v118, v119
	s_nop 0
	global_store_dwordx2 v244, v[234:235], s[20:21] offset:3072
	v_mul_f32_e32 v120, v120, v233
	v_mul_f32_e32 v121, v121, v233
	v_mul_f32_e32 v122, v122, v233
	v_mul_f32_e32 v123, v123, v233
	v_mul_f32_e32 v120, v136, v120
	v_mul_f32_e32 v121, v137, v121
	v_mul_f32_e32 v122, v138, v122
	v_mul_f32_e32 v123, v139, v123
	v_fma_f32 v120, v120, v212, v152
	v_fma_f32 v121, v121, v213, v153
	v_fma_f32 v122, v122, v214, v154
	v_fma_f32 v123, v123, v215, v155
	v_cvt_pk_bf16_f32 v234, v120, v121
	v_cvt_pk_bf16_f32 v235, v122, v123
	s_nop 0
	global_store_dwordx2 v244, v[234:235], s[22:23] offset:3072
	v_mul_f32_e32 v124, v124, v233
	v_mul_f32_e32 v125, v125, v233
	v_mul_f32_e32 v126, v126, v233
	v_mul_f32_e32 v127, v127, v233
	v_mul_f32_e32 v124, v140, v124
	v_mul_f32_e32 v125, v141, v125
	v_mul_f32_e32 v126, v142, v126
	v_mul_f32_e32 v127, v143, v127
	v_fma_f32 v124, v124, v216, v156
	v_fma_f32 v125, v125, v217, v157
	v_fma_f32 v126, v126, v218, v158
	v_fma_f32 v127, v127, v219, v159
	v_cvt_pk_bf16_f32 v234, v124, v125
	v_cvt_pk_bf16_f32 v235, v126, v127
	s_nop 0
	global_store_dwordx2 v244, v[234:235], s[24:25] offset:3072
	s_mov_b64 s[0:1], exec
